# static priority (guide 6.3) in all five GEMM K-loops: per-block s_setprio flips deleted, one static s_setprio 1 for waves 4..7 at K-loop entry, reset at exit
# speedup vs baseline: 1.0055x; 1.0001x over previous
; #define PG8_STAGE(bufoff, gbase, voff) do { _Pragma("unroll") for (int _i = 0; _i < 2; ++_i) \
;         __builtin_amdgcn_global_load_lds((const unsigned*)((const char*)(gbase) + (voff)[_i]), (PG8_LAS unsigned*)(lds + (bufoff) + ldsw + _i * 8192), 16, 0, 0); } while (0)
; #define PG8_LDA(dst, b, h) do { _Pragma("unroll") for (int m = 0; m < 4; ++m) _Pragma("unroll") for (int k = 0; k < 2; ++k) dst[m][k] = *(const PG8_LAS bf16x8*)(lds + PG8_SA(b, h) + aoff + m * 2048 + k * 1024); } while (0)
; #define PG8_LDB(dst, b, h) do { _Pragma("unroll") for (int n = 0; n < 2; ++n) _Pragma("unroll") for (int k = 0; k < 2; ++k) dst[n][k] = *(const PG8_LAS bf16x8*)(lds + PG8_SB(b, h) + boff + n * 2048 + k * 1024); } while (0)
; #define PG8_MMA(ai, bj, At, Bt) do { __builtin_amdgcn_s_setprio(1); _Pragma("unroll") for (int m = 0; m < 4; ++m) _Pragma("unroll") for (int n = 0; n < 2; ++n) _Pragma("unroll") for (int k = 0; k < 2; ++k) \
;         acc[ai][bj][m][n] = __builtin_amdgcn_mfma_f32_16x16x32_bf16(Bt[n][k], At[m][k], acc[ai][bj][m][n], 0, 0, 0); __builtin_amdgcn_s_setprio(0); } while (0)
; #define PG8_WAIT_V(n) asm volatile("s_waitcnt vmcnt(" #n ")" ::: "memory")
; #define PG8_WAIT_L(n) asm volatile("s_waitcnt lgkmcnt(" #n ")" ::: "memory")
; #define PG8_BAR __builtin_amdgcn_s_barrier()
; #define PG8_SCHED __builtin_amdgcn_sched_barrier(0)
; template <class Epi, class Sched, bool ALIGN_EPI = false, bool SP2 = false>
; __device__ __forceinline__ void gemm_phase(PG8_LAS unsigned char* lds, const Gemm g, const Sched& S, const Epi& E) {
;     ...
;             PG8_LDB(B0, 0, 0); PG8_LDB(B1, 0, 1); PG8_SCHED; PG8_LDA(At, 0, 0); PG8_STAGE(PG8_SA(1, 1), a1 + hstep, voffA);
;             PG8_WAIT_V(8); PG8_WAIT_L(0); PG8_BAR; PG8_MMA(0, 0, At, B0); PG8_MMA(0, 1, At, B1); PG8_BAR; PG8_SCHED;
;     ...
;         for (int a = 0; a < 2; ++a)
; #pragma unroll
;             for (int b = 0; b < 2; ++b)
; #pragma unroll
;                 for (int m = 0; m < 4; ++m)
; #pragma unroll
;                     for (int n = 0; n < 2; ++n) acc[a][b][m][n] = (f32x4){0.f, 0.f, 0.f, 0.f};
.LBB0_273:
	s_ashr_i32 s45, s44, 31
	s_lshl_b64 s[46:47], s[44:45], 19
	s_add_u32 s46, s3, s46
	s_addc_u32 s47, s4, s47
	s_and_b64 s[48:49], s[8:9], exec
	s_cselect_b32 s45, s47, s15
	s_cselect_b32 s89, s46, s14
	s_ashr_i32 s43, s42, 31
	s_lshl_b64 s[48:49], s[42:43], 19
	s_add_u32 s48, s5, s48
	s_addc_u32 s49, s28, s49
	s_and_b64 s[52:53], s[8:9], exec
	s_cselect_b32 s43, s49, s51
	s_cselect_b32 s90, s48, s50
	s_add_u32 s14, s14, 0x40080
	s_addc_u32 s15, s15, 0
	s_add_u32 s91, s50, 0x100
	v_mov_b32_e32 v0, 0
	s_addc_u32 s92, s51, 0
	s_mov_b32 s93, -2
	v_mov_b32_e32 v1, v0
	v_mov_b32_e32 v2, v0
	v_mov_b32_e32 v3, v0
	v_mov_b32_e32 v4, v0
	v_mov_b32_e32 v5, v0
	v_mov_b32_e32 v6, v0
	v_mov_b32_e32 v7, v0
	v_mov_b32_e32 v12, v0
	v_mov_b32_e32 v13, v0
	v_mov_b32_e32 v14, v0
	v_mov_b32_e32 v15, v0
	v_mov_b32_e32 v20, v0
	v_mov_b32_e32 v21, v0
	v_mov_b32_e32 v22, v0
	v_mov_b32_e32 v23, v0
	v_mov_b32_e32 v28, v0
	v_mov_b32_e32 v29, v0
	v_mov_b32_e32 v30, v0
	v_mov_b32_e32 v31, v0
	v_mov_b32_e32 v36, v0
	v_mov_b32_e32 v37, v0
	v_mov_b32_e32 v38, v0
	v_mov_b32_e32 v39, v0
	v_mov_b32_e32 v44, v0
	v_mov_b32_e32 v45, v0
	v_mov_b32_e32 v46, v0
	v_mov_b32_e32 v47, v0
	v_mov_b32_e32 v52, v0
	v_mov_b32_e32 v53, v0
	v_mov_b32_e32 v54, v0
	v_mov_b32_e32 v55, v0
	v_mov_b32_e32 v8, v0
	v_mov_b32_e32 v9, v0
	v_mov_b32_e32 v10, v0
	v_mov_b32_e32 v11, v0
	v_mov_b32_e32 v16, v0
	v_mov_b32_e32 v17, v0
	v_mov_b32_e32 v18, v0
	v_mov_b32_e32 v19, v0
	v_mov_b32_e32 v24, v0
	v_mov_b32_e32 v25, v0
	v_mov_b32_e32 v26, v0
	v_mov_b32_e32 v27, v0
	v_mov_b32_e32 v32, v0
	v_mov_b32_e32 v33, v0
	v_mov_b32_e32 v34, v0
	v_mov_b32_e32 v35, v0
	v_mov_b32_e32 v40, v0
	v_mov_b32_e32 v41, v0
	v_mov_b32_e32 v42, v0
	v_mov_b32_e32 v43, v0
	v_mov_b32_e32 v48, v0
	v_mov_b32_e32 v49, v0
	v_mov_b32_e32 v50, v0
	v_mov_b32_e32 v51, v0
	v_mov_b32_e32 v56, v0
	v_mov_b32_e32 v57, v0
	v_mov_b32_e32 v58, v0
	v_mov_b32_e32 v59, v0
	v_mov_b32_e32 v60, v0
	v_mov_b32_e32 v61, v0
	v_mov_b32_e32 v62, v0
	v_mov_b32_e32 v63, v0
	v_mov_b32_e32 v64, v0
	v_mov_b32_e32 v65, v0
	v_mov_b32_e32 v66, v0
	v_mov_b32_e32 v67, v0
	v_mov_b32_e32 v68, v0
	v_mov_b32_e32 v69, v0
	v_mov_b32_e32 v70, v0
	v_mov_b32_e32 v71, v0
	v_mov_b32_e32 v76, v0
	v_mov_b32_e32 v77, v0
	v_mov_b32_e32 v78, v0
	v_mov_b32_e32 v79, v0
	v_mov_b32_e32 v84, v0
	v_mov_b32_e32 v85, v0
	v_mov_b32_e32 v86, v0
	v_mov_b32_e32 v87, v0
	v_mov_b32_e32 v92, v0
	v_mov_b32_e32 v93, v0
	v_mov_b32_e32 v94, v0
	v_mov_b32_e32 v95, v0
	v_mov_b32_e32 v100, v0
	v_mov_b32_e32 v101, v0
	v_mov_b32_e32 v102, v0
	v_mov_b32_e32 v103, v0
	v_mov_b32_e32 v108, v0
	v_mov_b32_e32 v109, v0
	v_mov_b32_e32 v110, v0
	v_mov_b32_e32 v111, v0
	v_mov_b32_e32 v116, v0
	v_mov_b32_e32 v117, v0
	v_mov_b32_e32 v118, v0
	v_mov_b32_e32 v119, v0
	v_mov_b32_e32 v72, v0
	v_mov_b32_e32 v73, v0
	v_mov_b32_e32 v74, v0
	v_mov_b32_e32 v75, v0
	v_mov_b32_e32 v80, v0
	v_mov_b32_e32 v81, v0
	v_mov_b32_e32 v82, v0
	v_mov_b32_e32 v83, v0
	v_mov_b32_e32 v88, v0
	v_mov_b32_e32 v89, v0
	v_mov_b32_e32 v90, v0
	v_mov_b32_e32 v91, v0
	v_mov_b32_e32 v96, v0
	v_mov_b32_e32 v97, v0
	v_mov_b32_e32 v98, v0
	v_mov_b32_e32 v99, v0
	v_mov_b32_e32 v104, v0
	v_mov_b32_e32 v105, v0
	v_mov_b32_e32 v106, v0
	v_mov_b32_e32 v107, v0
	v_mov_b32_e32 v112, v0
	v_mov_b32_e32 v113, v0
	v_mov_b32_e32 v114, v0
	v_mov_b32_e32 v115, v0
	v_mov_b32_e32 v120, v0
	v_mov_b32_e32 v121, v0
	v_mov_b32_e32 v122, v0
	v_mov_b32_e32 v123, v0
	v_mov_b32_e32 v124, v0
	v_mov_b32_e32 v125, v0
	v_mov_b32_e32 v126, v0
	v_mov_b32_e32 v127, v0
	v_readfirstlane_b32 s32, v208
	s_cmp_ge_u32 s32, 256
	s_cbranch_scc0 .Lprio2_done
	s_setprio 1
.Lprio2_done:
.LBB0_274:
	s_lshr_b32 s32, s21, 1
	s_cmp_eq_u32 s32, 2
	s_cbranch_scc1 .Lp2_vloop
	ds_read_b128 v[146:149], v169
	ds_read_b128 v[150:153], v169 offset:1024
	ds_read_b128 v[178:181], v169 offset:2048
	ds_read_b128 v[182:185], v169 offset:3072
	ds_read_b128 v[186:189], v170
	ds_read_b128 v[190:193], v170 offset:1024
	ds_read_b128 v[194:197], v170 offset:2048
	ds_read_b128 v[198:201], v170 offset:3072
	s_add_u32 s0, s14, 0xfffc0080
	s_addc_u32 s1, s15, -1
	s_cmp_eq_u32 s93, 12
	s_cselect_b32 s53, s45, s1
	s_cselect_b32 s52, s89, s0
	s_cselect_b32 s51, s43, s92
	s_cselect_b32 s50, s90, s91
	v_lshl_add_u64 v[206:207], s[14:15], 0, v[138:139]
	s_add_i32 m0, s56, 0xc000
	ds_read_b128 v[202:205], v171
	ds_read_b128 v[210:213], v171 offset:1024
	ds_read_b128 v[214:217], v171 offset:2048
	ds_read_b128 v[218:221], v171 offset:3072
	ds_read_b128 v[222:225], v171 offset:4096
	ds_read_b128 v[226:229], v171 offset:5120
	ds_read_b128 v[230:233], v171 offset:6144
	ds_read_b128 v[234:237], v171 offset:7168
	global_load_lds_dwordx4 v[206:207], off
	v_lshl_add_u64 v[206:207], s[14:15], 0, v[140:141]
	s_add_i32 m0, s56, 0xe000
	s_nop 0
	global_load_lds_dwordx4 v[206:207], off
	s_waitcnt vmcnt(8)
	s_waitcnt lgkmcnt(0)
	s_barrier
; #define PG8_STAGE(bufoff, gbase, voff) do { _Pragma("unroll") for (int _i = 0; _i < 2; ++_i) \
;         __builtin_amdgcn_global_load_lds((const unsigned*)((const char*)(gbase) + (voff)[_i]), (PG8_LAS unsigned*)(lds + (bufoff) + ldsw + _i * 8192), 16, 0, 0); } while (0)
; #define PG8_LDA(dst, b, h) do { _Pragma("unroll") for (int m = 0; m < 4; ++m) _Pragma("unroll") for (int k = 0; k < 2; ++k) dst[m][k] = *(const PG8_LAS bf16x8*)(lds + PG8_SA(b, h) + aoff + m * 2048 + k * 1024); } while (0)
; #define PG8_MMA(ai, bj, At, Bt) do { __builtin_amdgcn_s_setprio(1); _Pragma("unroll") for (int m = 0; m < 4; ++m) _Pragma("unroll") for (int n = 0; n < 2; ++n) _Pragma("unroll") for (int k = 0; k < 2; ++k) \
;         acc[ai][bj][m][n] = __builtin_amdgcn_mfma_f32_16x16x32_bf16(Bt[n][k], At[m][k], acc[ai][bj][m][n], 0, 0, 0); __builtin_amdgcn_s_setprio(0); } while (0)
; #define PG8_WAIT_V(n) asm volatile("s_waitcnt vmcnt(" #n ")" ::: "memory")
; #define PG8_WAIT_L(n) asm volatile("s_waitcnt lgkmcnt(" #n ")" ::: "memory")
; #define PG8_BAR __builtin_amdgcn_s_barrier()
; #define PG8_SCHED __builtin_amdgcn_sched_barrier(0)
; template <class Epi, class Sched, bool ALIGN_EPI = false, bool SP2 = false>
; __device__ __forceinline__ void gemm_phase(PG8_LAS unsigned char* lds, const Gemm g, const Sched& S, const Epi& E) {
;     ...
;             PG8_WAIT_V(8); PG8_WAIT_L(0); PG8_BAR; PG8_MMA(0, 0, At, B0); PG8_MMA(0, 1, At, B1); PG8_BAR; PG8_SCHED;
;             PG8_LDA(At, 0, 1); PG8_STAGE(PG8_SB(0, 0), b2, voffB); PG8_STAGE(PG8_SB(0, 1), b2 + hstep, voffB); PG8_STAGE(PG8_SA(0, 0), a2, voffA);
;             PG8_WAIT_V(8); PG8_WAIT_L(0); PG8_BAR; PG8_MMA(1, 0, At, B0); PG8_MMA(1, 1, At, B1); PG8_BAR; PG8_SCHED;
	s_waitcnt lgkmcnt(0)
	v_mfma_f32_16x16x32_bf16 v[124:127], v[146:149], v[202:205], v[124:127]
	v_mfma_f32_16x16x32_bf16 v[120:123], v[178:181], v[202:205], v[120:123]
	v_mfma_f32_16x16x32_bf16 v[112:115], v[146:149], v[214:217], v[112:115]
	v_mfma_f32_16x16x32_bf16 v[104:107], v[178:181], v[214:217], v[104:107]
	v_mfma_f32_16x16x32_bf16 v[96:99], v[146:149], v[222:225], v[96:99]
	v_mfma_f32_16x16x32_bf16 v[88:91], v[178:181], v[222:225], v[88:91]
	v_mfma_f32_16x16x32_bf16 v[80:83], v[146:149], v[230:233], v[80:83]
	v_mfma_f32_16x16x32_bf16 v[72:75], v[178:181], v[230:233], v[72:75]
	v_mfma_f32_16x16x32_bf16 v[124:127], v[150:153], v[210:213], v[124:127]
	v_mfma_f32_16x16x32_bf16 v[120:123], v[182:185], v[210:213], v[120:123]
	v_mfma_f32_16x16x32_bf16 v[112:115], v[150:153], v[218:221], v[112:115]
	v_mfma_f32_16x16x32_bf16 v[104:107], v[182:185], v[218:221], v[104:107]
	v_mfma_f32_16x16x32_bf16 v[96:99], v[150:153], v[226:229], v[96:99]
	v_mfma_f32_16x16x32_bf16 v[88:91], v[182:185], v[226:229], v[88:91]
	v_mfma_f32_16x16x32_bf16 v[80:83], v[150:153], v[234:237], v[80:83]
	v_mfma_f32_16x16x32_bf16 v[72:75], v[182:185], v[234:237], v[72:75]
	v_mfma_f32_16x16x32_bf16 v[116:119], v[186:189], v[202:205], v[116:119]
	v_mfma_f32_16x16x32_bf16 v[108:111], v[194:197], v[202:205], v[108:111]
	v_mfma_f32_16x16x32_bf16 v[100:103], v[186:189], v[214:217], v[100:103]
	v_mfma_f32_16x16x32_bf16 v[92:95], v[194:197], v[214:217], v[92:95]
	v_mfma_f32_16x16x32_bf16 v[84:87], v[186:189], v[222:225], v[84:87]
	v_mfma_f32_16x16x32_bf16 v[76:79], v[194:197], v[222:225], v[76:79]
	v_mfma_f32_16x16x32_bf16 v[68:71], v[186:189], v[230:233], v[68:71]
	v_mfma_f32_16x16x32_bf16 v[64:67], v[194:197], v[230:233], v[64:67]
	v_mfma_f32_16x16x32_bf16 v[116:119], v[190:193], v[210:213], v[116:119]
	v_mfma_f32_16x16x32_bf16 v[108:111], v[198:201], v[210:213], v[108:111]
	v_mfma_f32_16x16x32_bf16 v[100:103], v[190:193], v[218:221], v[100:103]
	v_mfma_f32_16x16x32_bf16 v[92:95], v[198:201], v[218:221], v[92:95]
	v_mfma_f32_16x16x32_bf16 v[84:87], v[190:193], v[226:229], v[84:87]
	v_mfma_f32_16x16x32_bf16 v[76:79], v[198:201], v[226:229], v[76:79]
	v_mfma_f32_16x16x32_bf16 v[68:71], v[190:193], v[234:237], v[68:71]
	v_mfma_f32_16x16x32_bf16 v[64:67], v[198:201], v[234:237], v[64:67]
	s_barrier
	s_add_i32 s0, s74, s29
	v_lshl_add_u64 v[206:207], s[50:51], 0, v[132:133]
	s_mov_b32 m0, s0
	ds_read_b128 v[202:205], v171 offset:16384
	ds_read_b128 v[210:213], v171 offset:17408
	ds_read_b128 v[214:217], v171 offset:18432
	ds_read_b128 v[218:221], v171 offset:19456
	ds_read_b128 v[222:225], v171 offset:20480
	ds_read_b128 v[226:229], v171 offset:21504
	ds_read_b128 v[230:233], v171 offset:22528
	ds_read_b128 v[234:237], v171 offset:23552
	global_load_lds_dwordx4 v[206:207], off
	s_add_i32 m0, s0, 0x2000
	s_add_u32 s94, s50, 0x40000
	v_lshl_add_u64 v[238:239], s[50:51], 0, v[128:129]
	s_addc_u32 s95, s51, 0
	s_add_i32 s0, s75, s29
	global_load_lds_dwordx4 v[238:239], off
	v_lshl_add_u64 v[240:241], s[94:95], 0, v[132:133]
	s_mov_b32 m0, s0
	v_lshl_add_u64 v[242:243], s[52:53], 0, v[130:131]
	global_load_lds_dwordx4 v[240:241], off
	v_lshl_add_u64 v[240:241], s[94:95], 0, v[128:129]
	s_add_i32 m0, s0, 0x2000
	s_nop 0
	global_load_lds_dwordx4 v[240:241], off
	v_lshl_add_u64 v[240:241], s[52:53], 0, v[134:135]
	s_mov_b32 m0, s56
	s_nop 0
	global_load_lds_dwordx4 v[240:241], off
	s_mov_b32 m0, s57
	s_nop 0
	global_load_lds_dwordx4 v[242:243], off
	s_waitcnt vmcnt(8)
	s_waitcnt lgkmcnt(0)
	s_barrier
	s_waitcnt lgkmcnt(0)
	v_mfma_f32_16x16x32_bf16 v[60:63], v[146:149], v[202:205], v[60:63]
	v_mfma_f32_16x16x32_bf16 v[56:59], v[178:181], v[202:205], v[56:59]
	v_mfma_f32_16x16x32_bf16 v[48:51], v[146:149], v[214:217], v[48:51]
	v_mfma_f32_16x16x32_bf16 v[40:43], v[178:181], v[214:217], v[40:43]
	v_mfma_f32_16x16x32_bf16 v[32:35], v[146:149], v[222:225], v[32:35]
	v_mfma_f32_16x16x32_bf16 v[24:27], v[178:181], v[222:225], v[24:27]
	v_mfma_f32_16x16x32_bf16 v[16:19], v[146:149], v[230:233], v[16:19]
	v_mfma_f32_16x16x32_bf16 v[8:11], v[178:181], v[230:233], v[8:11]
	v_mfma_f32_16x16x32_bf16 v[60:63], v[150:153], v[210:213], v[60:63]
	v_mfma_f32_16x16x32_bf16 v[56:59], v[182:185], v[210:213], v[56:59]
	v_mfma_f32_16x16x32_bf16 v[48:51], v[150:153], v[218:221], v[48:51]
	v_mfma_f32_16x16x32_bf16 v[40:43], v[182:185], v[218:221], v[40:43]
	v_mfma_f32_16x16x32_bf16 v[32:35], v[150:153], v[226:229], v[32:35]
	v_mfma_f32_16x16x32_bf16 v[24:27], v[182:185], v[226:229], v[24:27]
	v_mfma_f32_16x16x32_bf16 v[16:19], v[150:153], v[234:237], v[16:19]
	v_mfma_f32_16x16x32_bf16 v[8:11], v[182:185], v[234:237], v[8:11]
	v_mfma_f32_16x16x32_bf16 v[52:55], v[186:189], v[202:205], v[52:55]
	v_mfma_f32_16x16x32_bf16 v[44:47], v[194:197], v[202:205], v[44:47]
	v_mfma_f32_16x16x32_bf16 v[36:39], v[186:189], v[214:217], v[36:39]
	v_mfma_f32_16x16x32_bf16 v[28:31], v[194:197], v[214:217], v[28:31]
	v_mfma_f32_16x16x32_bf16 v[20:23], v[186:189], v[222:225], v[20:23]
	v_mfma_f32_16x16x32_bf16 v[12:15], v[194:197], v[222:225], v[12:15]
	v_mfma_f32_16x16x32_bf16 v[4:7], v[186:189], v[230:233], v[4:7]
	v_mfma_f32_16x16x32_bf16 v[0:3], v[194:197], v[230:233], v[0:3]
	v_mfma_f32_16x16x32_bf16 v[52:55], v[190:193], v[210:213], v[52:55]
	v_mfma_f32_16x16x32_bf16 v[44:47], v[198:201], v[210:213], v[44:47]
	v_mfma_f32_16x16x32_bf16 v[36:39], v[190:193], v[218:221], v[36:39]
	v_mfma_f32_16x16x32_bf16 v[28:31], v[198:201], v[218:221], v[28:31]
	v_mfma_f32_16x16x32_bf16 v[20:23], v[190:193], v[226:229], v[20:23]
	v_mfma_f32_16x16x32_bf16 v[12:15], v[198:201], v[226:229], v[12:15]
	v_mfma_f32_16x16x32_bf16 v[4:7], v[190:193], v[234:237], v[4:7]
	v_mfma_f32_16x16x32_bf16 v[0:3], v[198:201], v[234:237], v[0:3]
	s_barrier
; #define PG8_STAGE(bufoff, gbase, voff) do { _Pragma("unroll") for (int _i = 0; _i < 2; ++_i) \
;         __builtin_amdgcn_global_load_lds((const unsigned*)((const char*)(gbase) + (voff)[_i]), (PG8_LAS unsigned*)(lds + (bufoff) + ldsw + _i * 8192), 16, 0, 0); } while (0)
; #define PG8_LDA(dst, b, h) do { _Pragma("unroll") for (int m = 0; m < 4; ++m) _Pragma("unroll") for (int k = 0; k < 2; ++k) dst[m][k] = *(const PG8_LAS bf16x8*)(lds + PG8_SA(b, h) + aoff + m * 2048 + k * 1024); } while (0)
; #define PG8_LDB(dst, b, h) do { _Pragma("unroll") for (int n = 0; n < 2; ++n) _Pragma("unroll") for (int k = 0; k < 2; ++k) dst[n][k] = *(const PG8_LAS bf16x8*)(lds + PG8_SB(b, h) + boff + n * 2048 + k * 1024); } while (0)
; #define PG8_MMA(ai, bj, At, Bt) do { __builtin_amdgcn_s_setprio(1); _Pragma("unroll") for (int m = 0; m < 4; ++m) _Pragma("unroll") for (int n = 0; n < 2; ++n) _Pragma("unroll") for (int k = 0; k < 2; ++k) \
;         acc[ai][bj][m][n] = __builtin_amdgcn_mfma_f32_16x16x32_bf16(Bt[n][k], At[m][k], acc[ai][bj][m][n], 0, 0, 0); __builtin_amdgcn_s_setprio(0); } while (0)
; #define PG8_WAIT_V(n) asm volatile("s_waitcnt vmcnt(" #n ")" ::: "memory")
; #define PG8_WAIT_L(n) asm volatile("s_waitcnt lgkmcnt(" #n ")" ::: "memory")
; #define PG8_BAR __builtin_amdgcn_s_barrier()
; #define PG8_SCHED __builtin_amdgcn_sched_barrier(0)
; template <class Epi, class Sched, bool ALIGN_EPI = false, bool SP2 = false>
; __device__ __forceinline__ void gemm_phase(PG8_LAS unsigned char* lds, const Gemm g, const Sched& S, const Epi& E) {
;     ...
;             PG8_WAIT_V(8); PG8_WAIT_L(0); PG8_BAR; PG8_MMA(1, 0, At, B0); PG8_MMA(1, 1, At, B1); PG8_BAR; PG8_SCHED;
;             PG8_LDB(B0, 1, 0); PG8_LDB(B1, 1, 1); PG8_SCHED; PG8_LDA(At, 1, 0); PG8_STAGE(PG8_SA(0, 1), a2 + hstep, voffA);
;             PG8_WAIT_V(8); PG8_WAIT_L(0); PG8_BAR; PG8_MMA(0, 0, At, B0); PG8_MMA(0, 1, At, B1); PG8_BAR; PG8_SCHED;
;             PG8_LDA(At, 1, 1); PG8_STAGE(PG8_SB(1, 0), b3, voffB); PG8_STAGE(PG8_SB(1, 1), b3 + hstep, voffB); PG8_STAGE(PG8_SA(1, 0), a3, voffA);
;             PG8_WAIT_V(8); PG8_WAIT_L(0); PG8_BAR; PG8_MMA(1, 0, At, B0); PG8_MMA(1, 1, At, B1); PG8_BAR; PG8_SCHED;
	s_add_i32 s0, 0, 0x18000
	v_add_u32_e32 v136, s0, v158
	s_add_i32 s1, 0, 0x1c000
	ds_read_b128 v[146:149], v136
	ds_read_b128 v[150:153], v136 offset:1024
	ds_read_b128 v[178:181], v136 offset:2048
	ds_read_b128 v[182:185], v136 offset:3072
	v_add_u32_e32 v136, s1, v158
	ds_read_b128 v[186:189], v136
	ds_read_b128 v[190:193], v136 offset:1024
	ds_read_b128 v[194:197], v136 offset:2048
	ds_read_b128 v[198:201], v136 offset:3072
	s_add_u32 s52, s52, 0x40000
	s_addc_u32 s53, s53, 0
	s_mov_b32 m0, s59
	v_lshl_add_u64 v[244:245], s[52:53], 0, v[134:135]
	ds_read_b128 v[202:205], v171 offset:32768
	ds_read_b128 v[210:213], v171 offset:33792
	ds_read_b128 v[214:217], v171 offset:34816
	ds_read_b128 v[218:221], v171 offset:35840
	ds_read_b128 v[222:225], v171 offset:36864
	ds_read_b128 v[226:229], v171 offset:37888
	ds_read_b128 v[230:233], v171 offset:38912
	ds_read_b128 v[234:237], v171 offset:39936
	global_load_lds_dwordx4 v[244:245], off
	v_lshl_add_u64 v[244:245], s[52:53], 0, v[130:131]
	s_mov_b32 m0, s60
	s_nop 0
	global_load_lds_dwordx4 v[244:245], off
	s_waitcnt vmcnt(8)
	s_waitcnt lgkmcnt(0)
	s_barrier
	s_waitcnt lgkmcnt(0)
	v_mfma_f32_16x16x32_bf16 v[124:127], v[146:149], v[202:205], v[124:127]
	v_mfma_f32_16x16x32_bf16 v[120:123], v[178:181], v[202:205], v[120:123]
	v_mfma_f32_16x16x32_bf16 v[112:115], v[146:149], v[214:217], v[112:115]
	v_mfma_f32_16x16x32_bf16 v[104:107], v[178:181], v[214:217], v[104:107]
	v_mfma_f32_16x16x32_bf16 v[96:99], v[146:149], v[222:225], v[96:99]
	v_mfma_f32_16x16x32_bf16 v[88:91], v[178:181], v[222:225], v[88:91]
	v_mfma_f32_16x16x32_bf16 v[80:83], v[146:149], v[230:233], v[80:83]
	v_mfma_f32_16x16x32_bf16 v[72:75], v[178:181], v[230:233], v[72:75]
	v_mfma_f32_16x16x32_bf16 v[124:127], v[150:153], v[210:213], v[124:127]
	v_mfma_f32_16x16x32_bf16 v[120:123], v[182:185], v[210:213], v[120:123]
	v_mfma_f32_16x16x32_bf16 v[112:115], v[150:153], v[218:221], v[112:115]
	v_mfma_f32_16x16x32_bf16 v[104:107], v[182:185], v[218:221], v[104:107]
	v_mfma_f32_16x16x32_bf16 v[96:99], v[150:153], v[226:229], v[96:99]
	v_mfma_f32_16x16x32_bf16 v[88:91], v[182:185], v[226:229], v[88:91]
	v_mfma_f32_16x16x32_bf16 v[80:83], v[150:153], v[234:237], v[80:83]
	v_mfma_f32_16x16x32_bf16 v[72:75], v[182:185], v[234:237], v[72:75]
	v_mfma_f32_16x16x32_bf16 v[116:119], v[186:189], v[202:205], v[116:119]
	v_mfma_f32_16x16x32_bf16 v[108:111], v[194:197], v[202:205], v[108:111]
	v_mfma_f32_16x16x32_bf16 v[100:103], v[186:189], v[214:217], v[100:103]
	v_mfma_f32_16x16x32_bf16 v[92:95], v[194:197], v[214:217], v[92:95]
	v_mfma_f32_16x16x32_bf16 v[84:87], v[186:189], v[222:225], v[84:87]
	v_mfma_f32_16x16x32_bf16 v[76:79], v[194:197], v[222:225], v[76:79]
	v_mfma_f32_16x16x32_bf16 v[68:71], v[186:189], v[230:233], v[68:71]
	v_mfma_f32_16x16x32_bf16 v[64:67], v[194:197], v[230:233], v[64:67]
	v_mfma_f32_16x16x32_bf16 v[116:119], v[190:193], v[210:213], v[116:119]
	v_mfma_f32_16x16x32_bf16 v[108:111], v[198:201], v[210:213], v[108:111]
	v_mfma_f32_16x16x32_bf16 v[100:103], v[190:193], v[218:221], v[100:103]
	v_mfma_f32_16x16x32_bf16 v[92:95], v[198:201], v[218:221], v[92:95]
	v_mfma_f32_16x16x32_bf16 v[84:87], v[190:193], v[226:229], v[84:87]
	v_mfma_f32_16x16x32_bf16 v[76:79], v[198:201], v[226:229], v[76:79]
	v_mfma_f32_16x16x32_bf16 v[68:71], v[190:193], v[234:237], v[68:71]
	v_mfma_f32_16x16x32_bf16 v[64:67], v[198:201], v[234:237], v[64:67]
	s_barrier
	s_add_i32 s0, s0, s29
	v_lshl_add_u64 v[206:207], v[206:207], 0, s[38:39]
	s_mov_b32 m0, s0
	ds_read_b128 v[202:205], v171 offset:49152
	ds_read_b128 v[210:213], v171 offset:50176
	ds_read_b128 v[214:217], v171 offset:51200
	ds_read_b128 v[218:221], v171 offset:52224
	ds_read_b128 v[222:225], v171 offset:53248
	ds_read_b128 v[226:229], v171 offset:54272
	ds_read_b128 v[230:233], v171 offset:55296
	ds_read_b128 v[234:237], v171 offset:56320
	global_load_lds_dwordx4 v[206:207], off
	s_add_i32 m0, s0, 0x2000
	s_add_u32 s50, s50, 0x40080
	v_lshl_add_u64 v[206:207], v[238:239], 0, s[38:39]
	s_addc_u32 s51, s51, 0
	s_add_i32 s0, s1, s29
	global_load_lds_dwordx4 v[206:207], off
	v_lshl_add_u64 v[206:207], s[50:51], 0, v[132:133]
	s_mov_b32 m0, s0
	s_nop 0
	global_load_lds_dwordx4 v[206:207], off
	v_lshl_add_u64 v[206:207], s[50:51], 0, v[128:129]
	s_add_i32 m0, s0, 0x2000
	s_nop 0
	global_load_lds_dwordx4 v[206:207], off
	v_lshl_add_u64 v[206:207], v[240:241], 0, s[38:39]
	s_mov_b32 m0, s69
	s_nop 0
	global_load_lds_dwordx4 v[206:207], off
	v_lshl_add_u64 v[206:207], v[242:243], 0, s[38:39]
	s_mov_b32 m0, s70
	s_nop 0
	global_load_lds_dwordx4 v[206:207], off
	s_waitcnt vmcnt(8)
	s_waitcnt lgkmcnt(0)
	s_barrier
	s_waitcnt lgkmcnt(0)
	v_mfma_f32_16x16x32_bf16 v[60:63], v[146:149], v[202:205], v[60:63]
	v_mfma_f32_16x16x32_bf16 v[56:59], v[178:181], v[202:205], v[56:59]
	v_mfma_f32_16x16x32_bf16 v[48:51], v[146:149], v[214:217], v[48:51]
	v_mfma_f32_16x16x32_bf16 v[40:43], v[178:181], v[214:217], v[40:43]
	v_mfma_f32_16x16x32_bf16 v[32:35], v[146:149], v[222:225], v[32:35]
	v_mfma_f32_16x16x32_bf16 v[24:27], v[178:181], v[222:225], v[24:27]
	v_mfma_f32_16x16x32_bf16 v[16:19], v[146:149], v[230:233], v[16:19]
	v_mfma_f32_16x16x32_bf16 v[8:11], v[178:181], v[230:233], v[8:11]
	v_mfma_f32_16x16x32_bf16 v[60:63], v[150:153], v[210:213], v[60:63]
	v_mfma_f32_16x16x32_bf16 v[56:59], v[182:185], v[210:213], v[56:59]
	v_mfma_f32_16x16x32_bf16 v[48:51], v[150:153], v[218:221], v[48:51]
	v_mfma_f32_16x16x32_bf16 v[40:43], v[182:185], v[218:221], v[40:43]
	v_mfma_f32_16x16x32_bf16 v[32:35], v[150:153], v[226:229], v[32:35]
	v_mfma_f32_16x16x32_bf16 v[24:27], v[182:185], v[226:229], v[24:27]
	v_mfma_f32_16x16x32_bf16 v[16:19], v[150:153], v[234:237], v[16:19]
	v_mfma_f32_16x16x32_bf16 v[8:11], v[182:185], v[234:237], v[8:11]
	v_mfma_f32_16x16x32_bf16 v[52:55], v[186:189], v[202:205], v[52:55]
	v_mfma_f32_16x16x32_bf16 v[44:47], v[194:197], v[202:205], v[44:47]
	v_mfma_f32_16x16x32_bf16 v[36:39], v[186:189], v[214:217], v[36:39]
	v_mfma_f32_16x16x32_bf16 v[28:31], v[194:197], v[214:217], v[28:31]
	v_mfma_f32_16x16x32_bf16 v[20:23], v[186:189], v[222:225], v[20:23]
	v_mfma_f32_16x16x32_bf16 v[12:15], v[194:197], v[222:225], v[12:15]
	v_mfma_f32_16x16x32_bf16 v[4:7], v[186:189], v[230:233], v[4:7]
	v_mfma_f32_16x16x32_bf16 v[0:3], v[194:197], v[230:233], v[0:3]
	v_mfma_f32_16x16x32_bf16 v[52:55], v[190:193], v[210:213], v[52:55]
	v_mfma_f32_16x16x32_bf16 v[44:47], v[198:201], v[210:213], v[44:47]
	v_mfma_f32_16x16x32_bf16 v[36:39], v[190:193], v[218:221], v[36:39]
	v_mfma_f32_16x16x32_bf16 v[28:31], v[198:201], v[218:221], v[28:31]
	v_mfma_f32_16x16x32_bf16 v[20:23], v[190:193], v[226:229], v[20:23]
	v_mfma_f32_16x16x32_bf16 v[12:15], v[198:201], v[226:229], v[12:15]
	v_mfma_f32_16x16x32_bf16 v[4:7], v[190:193], v[234:237], v[4:7]
	v_mfma_f32_16x16x32_bf16 v[0:3], v[198:201], v[234:237], v[0:3]
	s_barrier
	s_add_i32 s93, s93, 2
	s_add_u32 s14, s14, 0x100
	s_addc_u32 s15, s15, 0
	s_add_u32 s91, s91, 0x100
	s_addc_u32 s92, s92, 0
	s_cmp_gt_u32 s93, 13
	s_cbranch_scc0 .LBB0_274
; #define PG8_BAR __builtin_amdgcn_s_barrier()
; template <class Epi, class Sched, bool ALIGN_EPI = false, bool SP2 = false>
; __device__ __forceinline__ void gemm_phase(PG8_LAS unsigned char* lds, const Gemm g, const Sched& S, const Epi& E) {
;     ...
;         if constexpr (ALIGN_EPI) { if (wr == 0) PG8_BAR; }
.Lp2_kexit:
	s_setprio 0
	s_and_b64 vcc, exec, s[40:41]
	s_cbranch_vccz .LBB0_277
	s_barrier

; #define PG8_STAGE(bufoff, gbase, voff) do { _Pragma("unroll") for (int _i = 0; _i < 2; ++_i) \
;         __builtin_amdgcn_global_load_lds((const unsigned*)((const char*)(gbase) + (voff)[_i]), (PG8_LAS unsigned*)(lds + (bufoff) + ldsw + _i * 8192), 16, 0, 0); } while (0)
; #define PG8_LDA(dst, b, h) do { _Pragma("unroll") for (int m = 0; m < 4; ++m) _Pragma("unroll") for (int k = 0; k < 2; ++k) dst[m][k] = *(const PG8_LAS bf16x8*)(lds + PG8_SA(b, h) + aoff + m * 2048 + k * 1024); } while (0)
; #define PG8_LDB(dst, b, h) do { _Pragma("unroll") for (int n = 0; n < 2; ++n) _Pragma("unroll") for (int k = 0; k < 2; ++k) dst[n][k] = *(const PG8_LAS bf16x8*)(lds + PG8_SB(b, h) + boff + n * 2048 + k * 1024); } while (0)
; #define PG8_MMA(ai, bj, At, Bt) do { __builtin_amdgcn_s_setprio(1); _Pragma("unroll") for (int m = 0; m < 4; ++m) _Pragma("unroll") for (int n = 0; n < 2; ++n) _Pragma("unroll") for (int k = 0; k < 2; ++k) \
;         acc[ai][bj][m][n] = __builtin_amdgcn_mfma_f32_16x16x32_bf16(Bt[n][k], At[m][k], acc[ai][bj][m][n], 0, 0, 0); __builtin_amdgcn_s_setprio(0); } while (0)
; #define PG8_WAIT_V(n) asm volatile("s_waitcnt vmcnt(" #n ")" ::: "memory")
; #define PG8_WAIT_L(n) asm volatile("s_waitcnt lgkmcnt(" #n ")" ::: "memory")
; #define PG8_BAR __builtin_amdgcn_s_barrier()
; #define PG8_SCHED __builtin_amdgcn_sched_barrier(0)
; template <class Epi, class Sched, bool ALIGN_EPI = false, bool SP2 = false>
; __device__ __forceinline__ void gemm_phase(PG8_LAS unsigned char* lds, const Gemm g, const Sched& S, const Epi& E) {
;     ...
;             PG8_LDB(B0, 0, 0); PG8_LDB(B1, 0, 1); PG8_SCHED; PG8_LDA(At, 0, 0); PG8_STAGE(PG8_SA(1, 1), a1 + hstep, voffA);
;             PG8_WAIT_V(8); PG8_WAIT_L(0); PG8_BAR; PG8_MMA(0, 0, At, B0); PG8_MMA(0, 1, At, B1); PG8_BAR; PG8_SCHED;
;             PG8_LDA(At, 0, 1); PG8_STAGE(PG8_SB(0, 0), b2, voffB); PG8_STAGE(PG8_SB(0, 1), b2 + hstep, voffB); PG8_STAGE(PG8_SA(0, 0), a2, voffA);
;             PG8_WAIT_V(8); PG8_WAIT_L(0); PG8_BAR; PG8_MMA(1, 0, At, B0); PG8_MMA(1, 1, At, B1); PG8_BAR; PG8_SCHED;
.Lp2_vloop:
	ds_read_b128 v[146:149], v169
	ds_read_b128 v[150:153], v169 offset:1024
	ds_read_b128 v[178:181], v169 offset:2048
	ds_read_b128 v[182:185], v169 offset:3072
	ds_read_b128 v[186:189], v170
	ds_read_b128 v[190:193], v170 offset:1024
	ds_read_b128 v[194:197], v170 offset:2048
	ds_read_b128 v[198:201], v170 offset:3072
	s_add_u32 s0, s14, 0xfffc0080
	s_addc_u32 s1, s15, -1
	s_cmp_eq_u32 s93, 12
	s_cselect_b32 s53, s45, s1
	s_cselect_b32 s52, s89, s0
	s_cselect_b32 s51, s43, s92
	s_cselect_b32 s50, s90, s91
	v_lshl_add_u64 v[206:207], s[14:15], 0, v[138:139]
	s_add_i32 m0, s56, 0xc000
	ds_read_b128 v[202:205], v171
	ds_read_b128 v[210:213], v171 offset:1024
	ds_read_b128 v[214:217], v171 offset:2048
	ds_read_b128 v[218:221], v171 offset:3072
	ds_read_b128 v[222:225], v171 offset:4096
	ds_read_b128 v[226:229], v171 offset:5120
	ds_read_b128 v[230:233], v171 offset:6144
	ds_read_b128 v[234:237], v171 offset:7168
	global_load_lds_dwordx4 v[206:207], off
	v_lshl_add_u64 v[206:207], s[14:15], 0, v[140:141]
	s_add_i32 m0, s56, 0xe000
	s_nop 0
	global_load_lds_dwordx4 v[206:207], off
	s_waitcnt vmcnt(8)
	s_waitcnt lgkmcnt(0)
	s_barrier
	s_waitcnt lgkmcnt(0)
	v_mfma_f32_16x16x32_bf16 v[124:127], v[202:205], v[146:149], v[124:127]
	v_mfma_f32_16x16x32_bf16 v[120:123], v[202:205], v[178:181], v[120:123]
	v_mfma_f32_16x16x32_bf16 v[112:115], v[214:217], v[146:149], v[112:115]
	v_mfma_f32_16x16x32_bf16 v[104:107], v[214:217], v[178:181], v[104:107]
	v_mfma_f32_16x16x32_bf16 v[96:99], v[222:225], v[146:149], v[96:99]
	v_mfma_f32_16x16x32_bf16 v[88:91], v[222:225], v[178:181], v[88:91]
	v_mfma_f32_16x16x32_bf16 v[80:83], v[230:233], v[146:149], v[80:83]
	v_mfma_f32_16x16x32_bf16 v[72:75], v[230:233], v[178:181], v[72:75]
	v_mfma_f32_16x16x32_bf16 v[124:127], v[210:213], v[150:153], v[124:127]
	v_mfma_f32_16x16x32_bf16 v[120:123], v[210:213], v[182:185], v[120:123]
	v_mfma_f32_16x16x32_bf16 v[112:115], v[218:221], v[150:153], v[112:115]
	v_mfma_f32_16x16x32_bf16 v[104:107], v[218:221], v[182:185], v[104:107]
	v_mfma_f32_16x16x32_bf16 v[96:99], v[226:229], v[150:153], v[96:99]
	v_mfma_f32_16x16x32_bf16 v[88:91], v[226:229], v[182:185], v[88:91]
	v_mfma_f32_16x16x32_bf16 v[80:83], v[234:237], v[150:153], v[80:83]
	v_mfma_f32_16x16x32_bf16 v[72:75], v[234:237], v[182:185], v[72:75]
	v_mfma_f32_16x16x32_bf16 v[116:119], v[202:205], v[186:189], v[116:119]
	v_mfma_f32_16x16x32_bf16 v[108:111], v[202:205], v[194:197], v[108:111]
	v_mfma_f32_16x16x32_bf16 v[100:103], v[214:217], v[186:189], v[100:103]
	v_mfma_f32_16x16x32_bf16 v[92:95], v[214:217], v[194:197], v[92:95]
	v_mfma_f32_16x16x32_bf16 v[84:87], v[222:225], v[186:189], v[84:87]
	v_mfma_f32_16x16x32_bf16 v[76:79], v[222:225], v[194:197], v[76:79]
	v_mfma_f32_16x16x32_bf16 v[68:71], v[230:233], v[186:189], v[68:71]
	v_mfma_f32_16x16x32_bf16 v[64:67], v[230:233], v[194:197], v[64:67]
	v_mfma_f32_16x16x32_bf16 v[116:119], v[210:213], v[190:193], v[116:119]
	v_mfma_f32_16x16x32_bf16 v[108:111], v[210:213], v[198:201], v[108:111]
	v_mfma_f32_16x16x32_bf16 v[100:103], v[218:221], v[190:193], v[100:103]
	v_mfma_f32_16x16x32_bf16 v[92:95], v[218:221], v[198:201], v[92:95]
	v_mfma_f32_16x16x32_bf16 v[84:87], v[226:229], v[190:193], v[84:87]
	v_mfma_f32_16x16x32_bf16 v[76:79], v[226:229], v[198:201], v[76:79]
	v_mfma_f32_16x16x32_bf16 v[68:71], v[234:237], v[190:193], v[68:71]
	v_mfma_f32_16x16x32_bf16 v[64:67], v[234:237], v[198:201], v[64:67]
	s_barrier
	s_add_i32 s0, s74, s29
	v_lshl_add_u64 v[206:207], s[50:51], 0, v[132:133]
	s_mov_b32 m0, s0
	ds_read_b128 v[202:205], v171 offset:16384
	ds_read_b128 v[210:213], v171 offset:17408
	ds_read_b128 v[214:217], v171 offset:18432
	ds_read_b128 v[218:221], v171 offset:19456
	ds_read_b128 v[222:225], v171 offset:20480
	ds_read_b128 v[226:229], v171 offset:21504
	ds_read_b128 v[230:233], v171 offset:22528
	ds_read_b128 v[234:237], v171 offset:23552
	global_load_lds_dwordx4 v[206:207], off
	s_add_i32 m0, s0, 0x2000
	s_add_u32 s94, s50, 0x40000
	v_lshl_add_u64 v[238:239], s[50:51], 0, v[128:129]
	s_addc_u32 s95, s51, 0
	s_add_i32 s0, s75, s29
	global_load_lds_dwordx4 v[238:239], off
	v_lshl_add_u64 v[240:241], s[94:95], 0, v[132:133]
	s_mov_b32 m0, s0
	v_lshl_add_u64 v[242:243], s[52:53], 0, v[130:131]
	global_load_lds_dwordx4 v[240:241], off
	v_lshl_add_u64 v[240:241], s[94:95], 0, v[128:129]
	s_add_i32 m0, s0, 0x2000
	s_nop 0
	global_load_lds_dwordx4 v[240:241], off
	v_lshl_add_u64 v[240:241], s[52:53], 0, v[134:135]
	s_mov_b32 m0, s56
	s_nop 0
	global_load_lds_dwordx4 v[240:241], off
	s_mov_b32 m0, s57
	s_nop 0
	global_load_lds_dwordx4 v[242:243], off
	s_waitcnt vmcnt(8)
	s_waitcnt lgkmcnt(0)
	s_barrier
; #define PG8_STAGE(bufoff, gbase, voff) do { _Pragma("unroll") for (int _i = 0; _i < 2; ++_i) \
;         __builtin_amdgcn_global_load_lds((const unsigned*)((const char*)(gbase) + (voff)[_i]), (PG8_LAS unsigned*)(lds + (bufoff) + ldsw + _i * 8192), 16, 0, 0); } while (0)
; #define PG8_LDA(dst, b, h) do { _Pragma("unroll") for (int m = 0; m < 4; ++m) _Pragma("unroll") for (int k = 0; k < 2; ++k) dst[m][k] = *(const PG8_LAS bf16x8*)(lds + PG8_SA(b, h) + aoff + m * 2048 + k * 1024); } while (0)
; #define PG8_LDB(dst, b, h) do { _Pragma("unroll") for (int n = 0; n < 2; ++n) _Pragma("unroll") for (int k = 0; k < 2; ++k) dst[n][k] = *(const PG8_LAS bf16x8*)(lds + PG8_SB(b, h) + boff + n * 2048 + k * 1024); } while (0)
; #define PG8_MMA(ai, bj, At, Bt) do { __builtin_amdgcn_s_setprio(1); _Pragma("unroll") for (int m = 0; m < 4; ++m) _Pragma("unroll") for (int n = 0; n < 2; ++n) _Pragma("unroll") for (int k = 0; k < 2; ++k) \
;         acc[ai][bj][m][n] = __builtin_amdgcn_mfma_f32_16x16x32_bf16(Bt[n][k], At[m][k], acc[ai][bj][m][n], 0, 0, 0); __builtin_amdgcn_s_setprio(0); } while (0)
; #define PG8_WAIT_V(n) asm volatile("s_waitcnt vmcnt(" #n ")" ::: "memory")
; #define PG8_WAIT_L(n) asm volatile("s_waitcnt lgkmcnt(" #n ")" ::: "memory")
; #define PG8_BAR __builtin_amdgcn_s_barrier()
; #define PG8_SCHED __builtin_amdgcn_sched_barrier(0)
; template <class Epi, class Sched, bool ALIGN_EPI = false, bool SP2 = false>
; __device__ __forceinline__ void gemm_phase(PG8_LAS unsigned char* lds, const Gemm g, const Sched& S, const Epi& E) {
;     ...
;             PG8_WAIT_V(8); PG8_WAIT_L(0); PG8_BAR; PG8_MMA(1, 0, At, B0); PG8_MMA(1, 1, At, B1); PG8_BAR; PG8_SCHED;
;             PG8_LDB(B0, 1, 0); PG8_LDB(B1, 1, 1); PG8_SCHED; PG8_LDA(At, 1, 0); PG8_STAGE(PG8_SA(0, 1), a2 + hstep, voffA);
;             PG8_WAIT_V(8); PG8_WAIT_L(0); PG8_BAR; PG8_MMA(0, 0, At, B0); PG8_MMA(0, 1, At, B1); PG8_BAR; PG8_SCHED;
	s_waitcnt lgkmcnt(0)
	v_mfma_f32_16x16x32_bf16 v[60:63], v[202:205], v[146:149], v[60:63]
	v_mfma_f32_16x16x32_bf16 v[56:59], v[202:205], v[178:181], v[56:59]
	v_mfma_f32_16x16x32_bf16 v[48:51], v[214:217], v[146:149], v[48:51]
	v_mfma_f32_16x16x32_bf16 v[40:43], v[214:217], v[178:181], v[40:43]
	v_mfma_f32_16x16x32_bf16 v[32:35], v[222:225], v[146:149], v[32:35]
	v_mfma_f32_16x16x32_bf16 v[24:27], v[222:225], v[178:181], v[24:27]
	v_mfma_f32_16x16x32_bf16 v[16:19], v[230:233], v[146:149], v[16:19]
	v_mfma_f32_16x16x32_bf16 v[8:11], v[230:233], v[178:181], v[8:11]
	v_mfma_f32_16x16x32_bf16 v[60:63], v[210:213], v[150:153], v[60:63]
	v_mfma_f32_16x16x32_bf16 v[56:59], v[210:213], v[182:185], v[56:59]
	v_mfma_f32_16x16x32_bf16 v[48:51], v[218:221], v[150:153], v[48:51]
	v_mfma_f32_16x16x32_bf16 v[40:43], v[218:221], v[182:185], v[40:43]
	v_mfma_f32_16x16x32_bf16 v[32:35], v[226:229], v[150:153], v[32:35]
	v_mfma_f32_16x16x32_bf16 v[24:27], v[226:229], v[182:185], v[24:27]
	v_mfma_f32_16x16x32_bf16 v[16:19], v[234:237], v[150:153], v[16:19]
	v_mfma_f32_16x16x32_bf16 v[8:11], v[234:237], v[182:185], v[8:11]
	v_mfma_f32_16x16x32_bf16 v[52:55], v[202:205], v[186:189], v[52:55]
	v_mfma_f32_16x16x32_bf16 v[44:47], v[202:205], v[194:197], v[44:47]
	v_mfma_f32_16x16x32_bf16 v[36:39], v[214:217], v[186:189], v[36:39]
	v_mfma_f32_16x16x32_bf16 v[28:31], v[214:217], v[194:197], v[28:31]
	v_mfma_f32_16x16x32_bf16 v[20:23], v[222:225], v[186:189], v[20:23]
	v_mfma_f32_16x16x32_bf16 v[12:15], v[222:225], v[194:197], v[12:15]
	v_mfma_f32_16x16x32_bf16 v[4:7], v[230:233], v[186:189], v[4:7]
	v_mfma_f32_16x16x32_bf16 v[0:3], v[230:233], v[194:197], v[0:3]
	v_mfma_f32_16x16x32_bf16 v[52:55], v[210:213], v[190:193], v[52:55]
	v_mfma_f32_16x16x32_bf16 v[44:47], v[210:213], v[198:201], v[44:47]
	v_mfma_f32_16x16x32_bf16 v[36:39], v[218:221], v[190:193], v[36:39]
	v_mfma_f32_16x16x32_bf16 v[28:31], v[218:221], v[198:201], v[28:31]
	v_mfma_f32_16x16x32_bf16 v[20:23], v[226:229], v[190:193], v[20:23]
	v_mfma_f32_16x16x32_bf16 v[12:15], v[226:229], v[198:201], v[12:15]
	v_mfma_f32_16x16x32_bf16 v[4:7], v[234:237], v[190:193], v[4:7]
	v_mfma_f32_16x16x32_bf16 v[0:3], v[234:237], v[198:201], v[0:3]
	s_barrier
	s_add_i32 s0, 0, 0x18000
	v_add_u32_e32 v136, s0, v158
	s_add_i32 s1, 0, 0x1c000
	ds_read_b128 v[146:149], v136
	ds_read_b128 v[150:153], v136 offset:1024
	ds_read_b128 v[178:181], v136 offset:2048
	ds_read_b128 v[182:185], v136 offset:3072
	v_add_u32_e32 v136, s1, v158
	ds_read_b128 v[186:189], v136
	ds_read_b128 v[190:193], v136 offset:1024
	ds_read_b128 v[194:197], v136 offset:2048
	ds_read_b128 v[198:201], v136 offset:3072
	s_add_u32 s52, s52, 0x40000
	s_addc_u32 s53, s53, 0
	s_mov_b32 m0, s59
	v_lshl_add_u64 v[244:245], s[52:53], 0, v[134:135]
	ds_read_b128 v[202:205], v171 offset:32768
	ds_read_b128 v[210:213], v171 offset:33792
	ds_read_b128 v[214:217], v171 offset:34816
	ds_read_b128 v[218:221], v171 offset:35840
	ds_read_b128 v[222:225], v171 offset:36864
	ds_read_b128 v[226:229], v171 offset:37888
	ds_read_b128 v[230:233], v171 offset:38912
	ds_read_b128 v[234:237], v171 offset:39936
	global_load_lds_dwordx4 v[244:245], off
	v_lshl_add_u64 v[244:245], s[52:53], 0, v[130:131]
	s_mov_b32 m0, s60
	s_nop 0
	global_load_lds_dwordx4 v[244:245], off
	s_waitcnt vmcnt(8)
	s_waitcnt lgkmcnt(0)
	s_barrier
	s_waitcnt lgkmcnt(0)
	v_mfma_f32_16x16x32_bf16 v[124:127], v[202:205], v[146:149], v[124:127]
	v_mfma_f32_16x16x32_bf16 v[120:123], v[202:205], v[178:181], v[120:123]
	v_mfma_f32_16x16x32_bf16 v[112:115], v[214:217], v[146:149], v[112:115]
	v_mfma_f32_16x16x32_bf16 v[104:107], v[214:217], v[178:181], v[104:107]
	v_mfma_f32_16x16x32_bf16 v[96:99], v[222:225], v[146:149], v[96:99]
	v_mfma_f32_16x16x32_bf16 v[88:91], v[222:225], v[178:181], v[88:91]
	v_mfma_f32_16x16x32_bf16 v[80:83], v[230:233], v[146:149], v[80:83]
	v_mfma_f32_16x16x32_bf16 v[72:75], v[230:233], v[178:181], v[72:75]
	v_mfma_f32_16x16x32_bf16 v[124:127], v[210:213], v[150:153], v[124:127]
	v_mfma_f32_16x16x32_bf16 v[120:123], v[210:213], v[182:185], v[120:123]
	v_mfma_f32_16x16x32_bf16 v[112:115], v[218:221], v[150:153], v[112:115]
	v_mfma_f32_16x16x32_bf16 v[104:107], v[218:221], v[182:185], v[104:107]
	v_mfma_f32_16x16x32_bf16 v[96:99], v[226:229], v[150:153], v[96:99]
	v_mfma_f32_16x16x32_bf16 v[88:91], v[226:229], v[182:185], v[88:91]
	v_mfma_f32_16x16x32_bf16 v[80:83], v[234:237], v[150:153], v[80:83]
	v_mfma_f32_16x16x32_bf16 v[72:75], v[234:237], v[182:185], v[72:75]
	v_mfma_f32_16x16x32_bf16 v[116:119], v[202:205], v[186:189], v[116:119]
	v_mfma_f32_16x16x32_bf16 v[108:111], v[202:205], v[194:197], v[108:111]
	v_mfma_f32_16x16x32_bf16 v[100:103], v[214:217], v[186:189], v[100:103]
	v_mfma_f32_16x16x32_bf16 v[92:95], v[214:217], v[194:197], v[92:95]
	v_mfma_f32_16x16x32_bf16 v[84:87], v[222:225], v[186:189], v[84:87]
	v_mfma_f32_16x16x32_bf16 v[76:79], v[222:225], v[194:197], v[76:79]
	v_mfma_f32_16x16x32_bf16 v[68:71], v[230:233], v[186:189], v[68:71]
	v_mfma_f32_16x16x32_bf16 v[64:67], v[230:233], v[194:197], v[64:67]
	v_mfma_f32_16x16x32_bf16 v[116:119], v[210:213], v[190:193], v[116:119]
	v_mfma_f32_16x16x32_bf16 v[108:111], v[210:213], v[198:201], v[108:111]
	v_mfma_f32_16x16x32_bf16 v[100:103], v[218:221], v[190:193], v[100:103]
	v_mfma_f32_16x16x32_bf16 v[92:95], v[218:221], v[198:201], v[92:95]
	v_mfma_f32_16x16x32_bf16 v[84:87], v[226:229], v[190:193], v[84:87]
	v_mfma_f32_16x16x32_bf16 v[76:79], v[226:229], v[198:201], v[76:79]
	v_mfma_f32_16x16x32_bf16 v[68:71], v[234:237], v[190:193], v[68:71]
	v_mfma_f32_16x16x32_bf16 v[64:67], v[234:237], v[198:201], v[64:67]
	s_barrier
; #define PG8_STAGE(bufoff, gbase, voff) do { _Pragma("unroll") for (int _i = 0; _i < 2; ++_i) \
;         __builtin_amdgcn_global_load_lds((const unsigned*)((const char*)(gbase) + (voff)[_i]), (PG8_LAS unsigned*)(lds + (bufoff) + ldsw + _i * 8192), 16, 0, 0); } while (0)
; #define PG8_LDA(dst, b, h) do { _Pragma("unroll") for (int m = 0; m < 4; ++m) _Pragma("unroll") for (int k = 0; k < 2; ++k) dst[m][k] = *(const PG8_LAS bf16x8*)(lds + PG8_SA(b, h) + aoff + m * 2048 + k * 1024); } while (0)
; #define PG8_MMA(ai, bj, At, Bt) do { __builtin_amdgcn_s_setprio(1); _Pragma("unroll") for (int m = 0; m < 4; ++m) _Pragma("unroll") for (int n = 0; n < 2; ++n) _Pragma("unroll") for (int k = 0; k < 2; ++k) \
;         acc[ai][bj][m][n] = __builtin_amdgcn_mfma_f32_16x16x32_bf16(Bt[n][k], At[m][k], acc[ai][bj][m][n], 0, 0, 0); __builtin_amdgcn_s_setprio(0); } while (0)
; #define PG8_WAIT_V(n) asm volatile("s_waitcnt vmcnt(" #n ")" ::: "memory")
; #define PG8_WAIT_L(n) asm volatile("s_waitcnt lgkmcnt(" #n ")" ::: "memory")
; #define PG8_BAR __builtin_amdgcn_s_barrier()
; #define PG8_SCHED __builtin_amdgcn_sched_barrier(0)
; template <class Epi, class Sched, bool ALIGN_EPI = false, bool SP2 = false>
; __device__ __forceinline__ void gemm_phase(PG8_LAS unsigned char* lds, const Gemm g, const Sched& S, const Epi& E) {
;     ...
;             PG8_LDA(At, 1, 1); PG8_STAGE(PG8_SB(1, 0), b3, voffB); PG8_STAGE(PG8_SB(1, 1), b3 + hstep, voffB); PG8_STAGE(PG8_SA(1, 0), a3, voffA);
;             PG8_WAIT_V(8); PG8_WAIT_L(0); PG8_BAR; PG8_MMA(1, 0, At, B0); PG8_MMA(1, 1, At, B1); PG8_BAR; PG8_SCHED;
	s_add_i32 s0, s0, s29
	v_lshl_add_u64 v[206:207], v[206:207], 0, s[38:39]
	s_mov_b32 m0, s0
	ds_read_b128 v[202:205], v171 offset:49152
	ds_read_b128 v[210:213], v171 offset:50176
	ds_read_b128 v[214:217], v171 offset:51200
	ds_read_b128 v[218:221], v171 offset:52224
	ds_read_b128 v[222:225], v171 offset:53248
	ds_read_b128 v[226:229], v171 offset:54272
	ds_read_b128 v[230:233], v171 offset:55296
	ds_read_b128 v[234:237], v171 offset:56320
	global_load_lds_dwordx4 v[206:207], off
	s_add_i32 m0, s0, 0x2000
	s_add_u32 s50, s50, 0x40080
	v_lshl_add_u64 v[206:207], v[238:239], 0, s[38:39]
	s_addc_u32 s51, s51, 0
	s_add_i32 s0, s1, s29
	global_load_lds_dwordx4 v[206:207], off
	v_lshl_add_u64 v[206:207], s[50:51], 0, v[132:133]
	s_mov_b32 m0, s0
	s_nop 0
	global_load_lds_dwordx4 v[206:207], off
	v_lshl_add_u64 v[206:207], s[50:51], 0, v[128:129]
	s_add_i32 m0, s0, 0x2000
	s_nop 0
	global_load_lds_dwordx4 v[206:207], off
	v_lshl_add_u64 v[206:207], v[240:241], 0, s[38:39]
	s_mov_b32 m0, s69
	s_nop 0
	global_load_lds_dwordx4 v[206:207], off
	v_lshl_add_u64 v[206:207], v[242:243], 0, s[38:39]
	s_mov_b32 m0, s70
	s_nop 0
	global_load_lds_dwordx4 v[206:207], off
	s_waitcnt vmcnt(8)
	s_waitcnt lgkmcnt(0)
	s_barrier
	s_waitcnt lgkmcnt(0)
	v_mfma_f32_16x16x32_bf16 v[60:63], v[202:205], v[146:149], v[60:63]
	v_mfma_f32_16x16x32_bf16 v[56:59], v[202:205], v[178:181], v[56:59]
	v_mfma_f32_16x16x32_bf16 v[48:51], v[214:217], v[146:149], v[48:51]
	v_mfma_f32_16x16x32_bf16 v[40:43], v[214:217], v[178:181], v[40:43]
	v_mfma_f32_16x16x32_bf16 v[32:35], v[222:225], v[146:149], v[32:35]
	v_mfma_f32_16x16x32_bf16 v[24:27], v[222:225], v[178:181], v[24:27]
	v_mfma_f32_16x16x32_bf16 v[16:19], v[230:233], v[146:149], v[16:19]
	v_mfma_f32_16x16x32_bf16 v[8:11], v[230:233], v[178:181], v[8:11]
	v_mfma_f32_16x16x32_bf16 v[60:63], v[210:213], v[150:153], v[60:63]
	v_mfma_f32_16x16x32_bf16 v[56:59], v[210:213], v[182:185], v[56:59]
	v_mfma_f32_16x16x32_bf16 v[48:51], v[218:221], v[150:153], v[48:51]
	v_mfma_f32_16x16x32_bf16 v[40:43], v[218:221], v[182:185], v[40:43]
	v_mfma_f32_16x16x32_bf16 v[32:35], v[226:229], v[150:153], v[32:35]
	v_mfma_f32_16x16x32_bf16 v[24:27], v[226:229], v[182:185], v[24:27]
	v_mfma_f32_16x16x32_bf16 v[16:19], v[234:237], v[150:153], v[16:19]
	v_mfma_f32_16x16x32_bf16 v[8:11], v[234:237], v[182:185], v[8:11]
	v_mfma_f32_16x16x32_bf16 v[52:55], v[202:205], v[186:189], v[52:55]
	v_mfma_f32_16x16x32_bf16 v[44:47], v[202:205], v[194:197], v[44:47]
	v_mfma_f32_16x16x32_bf16 v[36:39], v[214:217], v[186:189], v[36:39]
	v_mfma_f32_16x16x32_bf16 v[28:31], v[214:217], v[194:197], v[28:31]
	v_mfma_f32_16x16x32_bf16 v[20:23], v[222:225], v[186:189], v[20:23]
	v_mfma_f32_16x16x32_bf16 v[12:15], v[222:225], v[194:197], v[12:15]
	v_mfma_f32_16x16x32_bf16 v[4:7], v[230:233], v[186:189], v[4:7]
	v_mfma_f32_16x16x32_bf16 v[0:3], v[230:233], v[194:197], v[0:3]
	v_mfma_f32_16x16x32_bf16 v[52:55], v[210:213], v[190:193], v[52:55]
	v_mfma_f32_16x16x32_bf16 v[44:47], v[210:213], v[198:201], v[44:47]
	v_mfma_f32_16x16x32_bf16 v[36:39], v[218:221], v[190:193], v[36:39]
	v_mfma_f32_16x16x32_bf16 v[28:31], v[218:221], v[198:201], v[28:31]
	v_mfma_f32_16x16x32_bf16 v[20:23], v[226:229], v[190:193], v[20:23]
	v_mfma_f32_16x16x32_bf16 v[12:15], v[226:229], v[198:201], v[12:15]
	v_mfma_f32_16x16x32_bf16 v[4:7], v[234:237], v[190:193], v[4:7]
	v_mfma_f32_16x16x32_bf16 v[0:3], v[234:237], v[198:201], v[0:3]
	s_barrier
	s_add_i32 s93, s93, 2
	s_add_u32 s14, s14, 0x100
	s_addc_u32 s15, s15, 0
	s_add_u32 s91, s91, 0x100
	s_addc_u32 s92, s92, 0
	s_cmp_gt_u32 s93, 13
	s_cbranch_scc0 .Lp2_vloop
	s_branch .Lp2_kexit

; #define PG8_STAGE(bufoff, gbase, voff) do { _Pragma("unroll") for (int _i = 0; _i < 2; ++_i) \
;         __builtin_amdgcn_global_load_lds((const unsigned*)((const char*)(gbase) + (voff)[_i]), (PG8_LAS unsigned*)(lds + (bufoff) + ldsw + _i * 8192), 16, 0, 0); } while (0)
; #define PG8_LDA(dst, b, h) do { _Pragma("unroll") for (int m = 0; m < 4; ++m) _Pragma("unroll") for (int k = 0; k < 2; ++k) dst[m][k] = *(const PG8_LAS bf16x8*)(lds + PG8_SA(b, h) + aoff + m * 2048 + k * 1024); } while (0)
; #define PG8_LDB(dst, b, h) do { _Pragma("unroll") for (int n = 0; n < 2; ++n) _Pragma("unroll") for (int k = 0; k < 2; ++k) dst[n][k] = *(const PG8_LAS bf16x8*)(lds + PG8_SB(b, h) + boff + n * 2048 + k * 1024); } while (0)
; #define PG8_MMA(ai, bj, At, Bt) do { __builtin_amdgcn_s_setprio(1); _Pragma("unroll") for (int m = 0; m < 4; ++m) _Pragma("unroll") for (int n = 0; n < 2; ++n) _Pragma("unroll") for (int k = 0; k < 2; ++k) \
;         acc[ai][bj][m][n] = __builtin_amdgcn_mfma_f32_16x16x32_bf16(Bt[n][k], At[m][k], acc[ai][bj][m][n], 0, 0, 0); __builtin_amdgcn_s_setprio(0); } while (0)
; #define PG8_WAIT_V(n) asm volatile("s_waitcnt vmcnt(" #n ")" ::: "memory")
; #define PG8_WAIT_L(n) asm volatile("s_waitcnt lgkmcnt(" #n ")" ::: "memory")
; #define PG8_BAR __builtin_amdgcn_s_barrier()
; #define PG8_SCHED __builtin_amdgcn_sched_barrier(0)
; template <class Epi, class Sched, bool ALIGN_EPI = false, bool SP2 = false>
; __device__ __forceinline__ void gemm_phase(PG8_LAS unsigned char* lds, const Gemm g, const Sched& S, const Epi& E) {
;     ...
;             PG8_LDB(B0, 0, 0); PG8_LDB(B1, 0, 1); PG8_SCHED; PG8_LDA(At, 0, 0); PG8_STAGE(PG8_SA(1, 1), a1 + hstep, voffA);
;             PG8_WAIT_V(8); PG8_WAIT_L(0); PG8_BAR; PG8_MMA(0, 0, At, B0); PG8_MMA(0, 1, At, B1); PG8_BAR; PG8_SCHED;
;     ...
;         for (int a = 0; a < 2; ++a)
; #pragma unroll
;             for (int b = 0; b < 2; ++b)
; #pragma unroll
;                 for (int m = 0; m < 4; ++m)
; #pragma unroll
;                     for (int n = 0; n < 2; ++n) acc[a][b][m][n] = (f32x4){0.f, 0.f, 0.f, 0.f};
.LBB0_457:
	s_ashr_i32 s49, s48, 31
	s_lshl_b64 s[50:51], s[48:49], 19
	s_add_u32 s50, s3, s50
	s_addc_u32 s51, s4, s51
	s_and_b64 s[52:53], s[10:11], exec
	s_cselect_b32 s15, s51, s55
	s_cselect_b32 s23, s50, s54
	s_ashr_i32 s47, s46, 31
	s_lshl_b64 s[52:53], s[46:47], 19
	s_add_u32 s52, s5, s52
	s_addc_u32 s53, s6, s53
	s_and_b64 s[58:59], s[10:11], exec
	s_cselect_b32 s47, s53, s57
	s_cselect_b32 s49, s52, s56
	s_add_u32 s54, s54, 0x40080
	s_addc_u32 s55, s55, 0
	s_add_u32 s75, s56, 0x100
	v_mov_b32_e32 v0, 0
	s_addc_u32 s76, s57, 0
	s_mov_b32 s77, -2
	s_waitcnt lgkmcnt(0)
	v_mov_b32_e32 v1, v0
	v_mov_b32_e32 v2, v0
	v_mov_b32_e32 v3, v0
	v_mov_b32_e32 v4, v0
	v_mov_b32_e32 v5, v0
	v_mov_b32_e32 v6, v0
	v_mov_b32_e32 v7, v0
	v_mov_b32_e32 v16, v0
	v_mov_b32_e32 v17, v0
	v_mov_b32_e32 v18, v0
	v_mov_b32_e32 v19, v0
	v_mov_b32_e32 v20, v0
	v_mov_b32_e32 v21, v0
	v_mov_b32_e32 v22, v0
	v_mov_b32_e32 v23, v0
	v_mov_b32_e32 v32, v0
	v_mov_b32_e32 v33, v0
	v_mov_b32_e32 v34, v0
	v_mov_b32_e32 v35, v0
	v_mov_b32_e32 v36, v0
	v_mov_b32_e32 v37, v0
	v_mov_b32_e32 v38, v0
	v_mov_b32_e32 v39, v0
	v_mov_b32_e32 v48, v0
	v_mov_b32_e32 v49, v0
	v_mov_b32_e32 v50, v0
	v_mov_b32_e32 v51, v0
	v_mov_b32_e32 v52, v0
	v_mov_b32_e32 v53, v0
	v_mov_b32_e32 v54, v0
	v_mov_b32_e32 v55, v0
	v_mov_b32_e32 v8, v0
	v_mov_b32_e32 v9, v0
	v_mov_b32_e32 v10, v0
	v_mov_b32_e32 v11, v0
	v_mov_b32_e32 v12, v0
	v_mov_b32_e32 v13, v0
	v_mov_b32_e32 v14, v0
	v_mov_b32_e32 v15, v0
	v_mov_b32_e32 v24, v0
	v_mov_b32_e32 v25, v0
	v_mov_b32_e32 v26, v0
	v_mov_b32_e32 v27, v0
	v_mov_b32_e32 v28, v0
	v_mov_b32_e32 v29, v0
	v_mov_b32_e32 v30, v0
	v_mov_b32_e32 v31, v0
	v_mov_b32_e32 v40, v0
	v_mov_b32_e32 v41, v0
	v_mov_b32_e32 v42, v0
	v_mov_b32_e32 v43, v0
	v_mov_b32_e32 v44, v0
	v_mov_b32_e32 v45, v0
	v_mov_b32_e32 v46, v0
	v_mov_b32_e32 v47, v0
	v_mov_b32_e32 v56, v0
	v_mov_b32_e32 v57, v0
	v_mov_b32_e32 v58, v0
	v_mov_b32_e32 v59, v0
	v_mov_b32_e32 v60, v0
	v_mov_b32_e32 v61, v0
	v_mov_b32_e32 v62, v0
	v_mov_b32_e32 v63, v0
	v_mov_b32_e32 v72, v0
	v_mov_b32_e32 v73, v0
	v_mov_b32_e32 v74, v0
	v_mov_b32_e32 v75, v0
	v_mov_b32_e32 v84, v0
	v_mov_b32_e32 v85, v0
	v_mov_b32_e32 v86, v0
	v_mov_b32_e32 v87, v0
	v_mov_b32_e32 v96, v0
	v_mov_b32_e32 v97, v0
	v_mov_b32_e32 v98, v0
	v_mov_b32_e32 v99, v0
	v_mov_b32_e32 v100, v0
	v_mov_b32_e32 v101, v0
	v_mov_b32_e32 v102, v0
	v_mov_b32_e32 v103, v0
	v_mov_b32_e32 v112, v0
	v_mov_b32_e32 v113, v0
	v_mov_b32_e32 v114, v0
	v_mov_b32_e32 v115, v0
	v_mov_b32_e32 v116, v0
	v_mov_b32_e32 v117, v0
	v_mov_b32_e32 v118, v0
	v_mov_b32_e32 v119, v0
	v_mov_b32_e32 v128, v0
	v_mov_b32_e32 v129, v0
	v_mov_b32_e32 v130, v0
	v_mov_b32_e32 v131, v0
	v_mov_b32_e32 v132, v0
	v_mov_b32_e32 v133, v0
	v_mov_b32_e32 v134, v0
	v_mov_b32_e32 v135, v0
	v_mov_b32_e32 v88, v0
	v_mov_b32_e32 v89, v0
	v_mov_b32_e32 v90, v0
	v_mov_b32_e32 v91, v0
	v_mov_b32_e32 v92, v0
	v_mov_b32_e32 v93, v0
	v_mov_b32_e32 v94, v0
	v_mov_b32_e32 v95, v0
	v_mov_b32_e32 v104, v0
	v_mov_b32_e32 v105, v0
	v_mov_b32_e32 v106, v0
	v_mov_b32_e32 v107, v0
	v_mov_b32_e32 v108, v0
	v_mov_b32_e32 v109, v0
	v_mov_b32_e32 v110, v0
	v_mov_b32_e32 v111, v0
	v_mov_b32_e32 v120, v0
	v_mov_b32_e32 v121, v0
	v_mov_b32_e32 v122, v0
	v_mov_b32_e32 v123, v0
	v_mov_b32_e32 v124, v0
	v_mov_b32_e32 v125, v0
	v_mov_b32_e32 v126, v0
	v_mov_b32_e32 v127, v0
	v_mov_b32_e32 v136, v0
	v_mov_b32_e32 v137, v0
	v_mov_b32_e32 v138, v0
	v_mov_b32_e32 v139, v0
	v_mov_b32_e32 v140, v0
	v_mov_b32_e32 v141, v0
	v_mov_b32_e32 v142, v0
	v_mov_b32_e32 v143, v0
	v_readfirstlane_b32 s32, v208
	s_cmp_ge_u32 s32, 256
	s_cbranch_scc0 .Lprio4_done
	s_setprio 1
.Lprio4_done:
.LBB0_458:
	ds_read_b128 v[64:67], v249
	ds_read_b128 v[68:71], v249 offset:1024
	ds_read_b128 v[76:79], v249 offset:2048
	ds_read_b128 v[80:83], v249 offset:3072
	ds_read_b128 v[144:147], v250
	ds_read_b128 v[148:151], v250 offset:1024
	ds_read_b128 v[152:155], v250 offset:2048
	ds_read_b128 v[156:159], v250 offset:3072
	s_add_u32 s0, s54, 0xfffc0080
	s_addc_u32 s1, s55, -1
	s_cmp_eq_u32 s77, 12
	s_cselect_b32 s59, s15, s1
	s_cselect_b32 s58, s23, s0
	s_cselect_b32 s57, s47, s76
	s_cselect_b32 s56, s49, s75
	v_lshl_add_u64 v[192:193], s[54:55], 0, v[220:221]
	s_add_i32 m0, s28, 0xc000
	ds_read_b128 v[160:163], v251
	ds_read_b128 v[164:167], v251 offset:1024
	ds_read_b128 v[168:171], v251 offset:2048
	ds_read_b128 v[172:175], v251 offset:3072
	ds_read_b128 v[176:179], v251 offset:4096
	ds_read_b128 v[180:183], v251 offset:5120
	ds_read_b128 v[184:187], v251 offset:6144
	ds_read_b128 v[188:191], v251 offset:7168
	global_load_lds_dwordx4 v[192:193], off
	v_lshl_add_u64 v[192:193], s[54:55], 0, v[222:223]
	s_add_i32 m0, s28, 0xe000
	s_nop 0
	global_load_lds_dwordx4 v[192:193], off
	s_waitcnt vmcnt(8)
	s_waitcnt lgkmcnt(0)
	s_barrier
; #define PG8_STAGE(bufoff, gbase, voff) do { _Pragma("unroll") for (int _i = 0; _i < 2; ++_i) \
;         __builtin_amdgcn_global_load_lds((const unsigned*)((const char*)(gbase) + (voff)[_i]), (PG8_LAS unsigned*)(lds + (bufoff) + ldsw + _i * 8192), 16, 0, 0); } while (0)
; #define PG8_LDA(dst, b, h) do { _Pragma("unroll") for (int m = 0; m < 4; ++m) _Pragma("unroll") for (int k = 0; k < 2; ++k) dst[m][k] = *(const PG8_LAS bf16x8*)(lds + PG8_SA(b, h) + aoff + m * 2048 + k * 1024); } while (0)
; #define PG8_MMA(ai, bj, At, Bt) do { __builtin_amdgcn_s_setprio(1); _Pragma("unroll") for (int m = 0; m < 4; ++m) _Pragma("unroll") for (int n = 0; n < 2; ++n) _Pragma("unroll") for (int k = 0; k < 2; ++k) \
;         acc[ai][bj][m][n] = __builtin_amdgcn_mfma_f32_16x16x32_bf16(Bt[n][k], At[m][k], acc[ai][bj][m][n], 0, 0, 0); __builtin_amdgcn_s_setprio(0); } while (0)
; #define PG8_WAIT_V(n) asm volatile("s_waitcnt vmcnt(" #n ")" ::: "memory")
; #define PG8_WAIT_L(n) asm volatile("s_waitcnt lgkmcnt(" #n ")" ::: "memory")
; #define PG8_BAR __builtin_amdgcn_s_barrier()
; #define PG8_SCHED __builtin_amdgcn_sched_barrier(0)
; template <class Epi, class Sched, bool ALIGN_EPI = false, bool SP2 = false>
; __device__ __forceinline__ void gemm_phase(PG8_LAS unsigned char* lds, const Gemm g, const Sched& S, const Epi& E) {
;     ...
;             PG8_WAIT_V(8); PG8_WAIT_L(0); PG8_BAR; PG8_MMA(0, 0, At, B0); PG8_MMA(0, 1, At, B1); PG8_BAR; PG8_SCHED;
;             PG8_LDA(At, 0, 1); PG8_STAGE(PG8_SB(0, 0), b2, voffB); PG8_STAGE(PG8_SB(0, 1), b2 + hstep, voffB); PG8_STAGE(PG8_SA(0, 0), a2, voffA);
;             PG8_WAIT_V(8); PG8_WAIT_L(0); PG8_BAR; PG8_MMA(1, 0, At, B0); PG8_MMA(1, 1, At, B1); PG8_BAR; PG8_SCHED;
	s_waitcnt lgkmcnt(0)
	v_mfma_f32_16x16x32_bf16 v[140:143], v[64:67], v[160:163], v[140:143]
	v_mfma_f32_16x16x32_bf16 v[136:139], v[76:79], v[160:163], v[136:139]
	v_mfma_f32_16x16x32_bf16 v[124:127], v[64:67], v[168:171], v[124:127]
	v_mfma_f32_16x16x32_bf16 v[120:123], v[76:79], v[168:171], v[120:123]
	v_mfma_f32_16x16x32_bf16 v[108:111], v[64:67], v[176:179], v[108:111]
	v_mfma_f32_16x16x32_bf16 v[104:107], v[76:79], v[176:179], v[104:107]
	v_mfma_f32_16x16x32_bf16 v[92:95], v[64:67], v[184:187], v[92:95]
	v_mfma_f32_16x16x32_bf16 v[88:91], v[76:79], v[184:187], v[88:91]
	v_mfma_f32_16x16x32_bf16 v[140:143], v[68:71], v[164:167], v[140:143]
	v_mfma_f32_16x16x32_bf16 v[136:139], v[80:83], v[164:167], v[136:139]
	v_mfma_f32_16x16x32_bf16 v[124:127], v[68:71], v[172:175], v[124:127]
	v_mfma_f32_16x16x32_bf16 v[120:123], v[80:83], v[172:175], v[120:123]
	v_mfma_f32_16x16x32_bf16 v[108:111], v[68:71], v[180:183], v[108:111]
	v_mfma_f32_16x16x32_bf16 v[104:107], v[80:83], v[180:183], v[104:107]
	v_mfma_f32_16x16x32_bf16 v[92:95], v[68:71], v[188:191], v[92:95]
	v_mfma_f32_16x16x32_bf16 v[88:91], v[80:83], v[188:191], v[88:91]
	v_mfma_f32_16x16x32_bf16 v[132:135], v[144:147], v[160:163], v[132:135]
	v_mfma_f32_16x16x32_bf16 v[128:131], v[152:155], v[160:163], v[128:131]
	v_mfma_f32_16x16x32_bf16 v[116:119], v[144:147], v[168:171], v[116:119]
	v_mfma_f32_16x16x32_bf16 v[112:115], v[152:155], v[168:171], v[112:115]
	v_mfma_f32_16x16x32_bf16 v[100:103], v[144:147], v[176:179], v[100:103]
	v_mfma_f32_16x16x32_bf16 v[96:99], v[152:155], v[176:179], v[96:99]
	v_mfma_f32_16x16x32_bf16 v[84:87], v[144:147], v[184:187], v[84:87]
	v_mfma_f32_16x16x32_bf16 v[72:75], v[152:155], v[184:187], v[72:75]
	v_mfma_f32_16x16x32_bf16 v[132:135], v[148:151], v[164:167], v[132:135]
	v_mfma_f32_16x16x32_bf16 v[128:131], v[156:159], v[164:167], v[128:131]
	v_mfma_f32_16x16x32_bf16 v[116:119], v[148:151], v[172:175], v[116:119]
	v_mfma_f32_16x16x32_bf16 v[112:115], v[156:159], v[172:175], v[112:115]
	v_mfma_f32_16x16x32_bf16 v[100:103], v[148:151], v[180:183], v[100:103]
	v_mfma_f32_16x16x32_bf16 v[96:99], v[156:159], v[180:183], v[96:99]
	v_mfma_f32_16x16x32_bf16 v[84:87], v[148:151], v[188:191], v[84:87]
	v_mfma_f32_16x16x32_bf16 v[72:75], v[156:159], v[188:191], v[72:75]
	s_barrier
	s_add_i32 s0, s70, s7
	v_lshl_add_u64 v[192:193], s[56:57], 0, v[212:213]
	s_mov_b32 m0, s0
	ds_read_b128 v[160:163], v251 offset:16384
	ds_read_b128 v[164:167], v251 offset:17408
	ds_read_b128 v[168:171], v251 offset:18432
	ds_read_b128 v[172:175], v251 offset:19456
	ds_read_b128 v[176:179], v251 offset:20480
	ds_read_b128 v[180:183], v251 offset:21504
	ds_read_b128 v[184:187], v251 offset:22528
	ds_read_b128 v[188:191], v251 offset:23552
	global_load_lds_dwordx4 v[192:193], off
	s_add_i32 m0, s0, 0x2000
	s_add_u32 s78, s56, 0x40000
	v_lshl_add_u64 v[194:195], s[56:57], 0, v[216:217]
	s_addc_u32 s79, s57, 0
	s_add_i32 s0, s71, s7
	global_load_lds_dwordx4 v[194:195], off
	v_lshl_add_u64 v[196:197], s[78:79], 0, v[212:213]
	s_mov_b32 m0, s0
	v_lshl_add_u64 v[198:199], s[58:59], 0, v[214:215]
	global_load_lds_dwordx4 v[196:197], off
	v_lshl_add_u64 v[196:197], s[78:79], 0, v[216:217]
	s_add_i32 m0, s0, 0x2000
	s_nop 0
	global_load_lds_dwordx4 v[196:197], off
	v_lshl_add_u64 v[196:197], s[58:59], 0, v[210:211]
	s_mov_b32 m0, s28
	s_nop 0
	global_load_lds_dwordx4 v[196:197], off
	s_mov_b32 m0, s29
	s_nop 0
	global_load_lds_dwordx4 v[198:199], off
	s_waitcnt vmcnt(8)
	s_waitcnt lgkmcnt(0)
	s_barrier
	s_waitcnt lgkmcnt(0)
	v_mfma_f32_16x16x32_bf16 v[60:63], v[64:67], v[160:163], v[60:63]
	v_mfma_f32_16x16x32_bf16 v[56:59], v[76:79], v[160:163], v[56:59]
	v_mfma_f32_16x16x32_bf16 v[44:47], v[64:67], v[168:171], v[44:47]
	v_mfma_f32_16x16x32_bf16 v[40:43], v[76:79], v[168:171], v[40:43]
	v_mfma_f32_16x16x32_bf16 v[28:31], v[64:67], v[176:179], v[28:31]
	v_mfma_f32_16x16x32_bf16 v[24:27], v[76:79], v[176:179], v[24:27]
	v_mfma_f32_16x16x32_bf16 v[12:15], v[64:67], v[184:187], v[12:15]
	v_mfma_f32_16x16x32_bf16 v[8:11], v[76:79], v[184:187], v[8:11]
	v_mfma_f32_16x16x32_bf16 v[60:63], v[68:71], v[164:167], v[60:63]
	v_mfma_f32_16x16x32_bf16 v[56:59], v[80:83], v[164:167], v[56:59]
	v_mfma_f32_16x16x32_bf16 v[44:47], v[68:71], v[172:175], v[44:47]
	v_mfma_f32_16x16x32_bf16 v[40:43], v[80:83], v[172:175], v[40:43]
	v_mfma_f32_16x16x32_bf16 v[28:31], v[68:71], v[180:183], v[28:31]
	v_mfma_f32_16x16x32_bf16 v[24:27], v[80:83], v[180:183], v[24:27]
	v_mfma_f32_16x16x32_bf16 v[12:15], v[68:71], v[188:191], v[12:15]
	v_mfma_f32_16x16x32_bf16 v[8:11], v[80:83], v[188:191], v[8:11]
	v_mfma_f32_16x16x32_bf16 v[52:55], v[144:147], v[160:163], v[52:55]
	v_mfma_f32_16x16x32_bf16 v[48:51], v[152:155], v[160:163], v[48:51]
	v_mfma_f32_16x16x32_bf16 v[36:39], v[144:147], v[168:171], v[36:39]
	v_mfma_f32_16x16x32_bf16 v[32:35], v[152:155], v[168:171], v[32:35]
	v_mfma_f32_16x16x32_bf16 v[20:23], v[144:147], v[176:179], v[20:23]
	v_mfma_f32_16x16x32_bf16 v[16:19], v[152:155], v[176:179], v[16:19]
	v_mfma_f32_16x16x32_bf16 v[4:7], v[144:147], v[184:187], v[4:7]
	v_mfma_f32_16x16x32_bf16 v[0:3], v[152:155], v[184:187], v[0:3]
	v_mfma_f32_16x16x32_bf16 v[52:55], v[148:151], v[164:167], v[52:55]
	v_mfma_f32_16x16x32_bf16 v[48:51], v[156:159], v[164:167], v[48:51]
	v_mfma_f32_16x16x32_bf16 v[36:39], v[148:151], v[172:175], v[36:39]
	v_mfma_f32_16x16x32_bf16 v[32:35], v[156:159], v[172:175], v[32:35]
	v_mfma_f32_16x16x32_bf16 v[20:23], v[148:151], v[180:183], v[20:23]
	v_mfma_f32_16x16x32_bf16 v[16:19], v[156:159], v[180:183], v[16:19]
	v_mfma_f32_16x16x32_bf16 v[4:7], v[148:151], v[188:191], v[4:7]
	v_mfma_f32_16x16x32_bf16 v[0:3], v[156:159], v[188:191], v[0:3]
	s_barrier
; #define PG8_STAGE(bufoff, gbase, voff) do { _Pragma("unroll") for (int _i = 0; _i < 2; ++_i) \
;         __builtin_amdgcn_global_load_lds((const unsigned*)((const char*)(gbase) + (voff)[_i]), (PG8_LAS unsigned*)(lds + (bufoff) + ldsw + _i * 8192), 16, 0, 0); } while (0)
; #define PG8_LDA(dst, b, h) do { _Pragma("unroll") for (int m = 0; m < 4; ++m) _Pragma("unroll") for (int k = 0; k < 2; ++k) dst[m][k] = *(const PG8_LAS bf16x8*)(lds + PG8_SA(b, h) + aoff + m * 2048 + k * 1024); } while (0)
; #define PG8_LDB(dst, b, h) do { _Pragma("unroll") for (int n = 0; n < 2; ++n) _Pragma("unroll") for (int k = 0; k < 2; ++k) dst[n][k] = *(const PG8_LAS bf16x8*)(lds + PG8_SB(b, h) + boff + n * 2048 + k * 1024); } while (0)
; #define PG8_MMA(ai, bj, At, Bt) do { __builtin_amdgcn_s_setprio(1); _Pragma("unroll") for (int m = 0; m < 4; ++m) _Pragma("unroll") for (int n = 0; n < 2; ++n) _Pragma("unroll") for (int k = 0; k < 2; ++k) \
;         acc[ai][bj][m][n] = __builtin_amdgcn_mfma_f32_16x16x32_bf16(Bt[n][k], At[m][k], acc[ai][bj][m][n], 0, 0, 0); __builtin_amdgcn_s_setprio(0); } while (0)
; #define PG8_WAIT_V(n) asm volatile("s_waitcnt vmcnt(" #n ")" ::: "memory")
; #define PG8_WAIT_L(n) asm volatile("s_waitcnt lgkmcnt(" #n ")" ::: "memory")
; #define PG8_BAR __builtin_amdgcn_s_barrier()
; #define PG8_SCHED __builtin_amdgcn_sched_barrier(0)
; template <class Epi, class Sched, bool ALIGN_EPI = false, bool SP2 = false>
; __device__ __forceinline__ void gemm_phase(PG8_LAS unsigned char* lds, const Gemm g, const Sched& S, const Epi& E) {
;     ...
;             PG8_LDB(B0, 1, 0); PG8_LDB(B1, 1, 1); PG8_SCHED; PG8_LDA(At, 1, 0); PG8_STAGE(PG8_SA(0, 1), a2 + hstep, voffA);
;             PG8_WAIT_V(8); PG8_WAIT_L(0); PG8_BAR; PG8_MMA(0, 0, At, B0); PG8_MMA(0, 1, At, B1); PG8_BAR; PG8_SCHED;
	s_add_i32 s0, 0, 0x18000
	s_add_i32 s1, 0, 0x1c000
	v_add_u32_e32 v80, s0, v247
	v_add_u32_e32 v156, s1, v247
	ds_read_b128 v[64:67], v80
	ds_read_b128 v[68:71], v80 offset:1024
	ds_read_b128 v[76:79], v80 offset:2048
	ds_read_b128 v[80:83], v80 offset:3072
	ds_read_b128 v[144:147], v156
	ds_read_b128 v[148:151], v156 offset:1024
	ds_read_b128 v[152:155], v156 offset:2048
	ds_read_b128 v[156:159], v156 offset:3072
	s_add_u32 s58, s58, 0x40000
	s_addc_u32 s59, s59, 0
	s_mov_b32 m0, s60
	v_lshl_add_u64 v[200:201], s[58:59], 0, v[210:211]
	ds_read_b128 v[160:163], v251 offset:32768
	ds_read_b128 v[164:167], v251 offset:33792
	ds_read_b128 v[168:171], v251 offset:34816
	ds_read_b128 v[172:175], v251 offset:35840
	ds_read_b128 v[176:179], v251 offset:36864
	ds_read_b128 v[180:183], v251 offset:37888
	ds_read_b128 v[184:187], v251 offset:38912
	ds_read_b128 v[188:191], v251 offset:39936
	global_load_lds_dwordx4 v[200:201], off
	v_lshl_add_u64 v[200:201], s[58:59], 0, v[214:215]
	s_mov_b32 m0, s61
	s_nop 0
	global_load_lds_dwordx4 v[200:201], off
	s_waitcnt vmcnt(8)
	s_waitcnt lgkmcnt(0)
	s_barrier
	s_waitcnt lgkmcnt(0)
	v_mfma_f32_16x16x32_bf16 v[140:143], v[64:67], v[160:163], v[140:143]
	v_mfma_f32_16x16x32_bf16 v[136:139], v[76:79], v[160:163], v[136:139]
	v_mfma_f32_16x16x32_bf16 v[124:127], v[64:67], v[168:171], v[124:127]
	v_mfma_f32_16x16x32_bf16 v[120:123], v[76:79], v[168:171], v[120:123]
	v_mfma_f32_16x16x32_bf16 v[108:111], v[64:67], v[176:179], v[108:111]
	v_mfma_f32_16x16x32_bf16 v[104:107], v[76:79], v[176:179], v[104:107]
	v_mfma_f32_16x16x32_bf16 v[92:95], v[64:67], v[184:187], v[92:95]
	v_mfma_f32_16x16x32_bf16 v[88:91], v[76:79], v[184:187], v[88:91]
	v_mfma_f32_16x16x32_bf16 v[140:143], v[68:71], v[164:167], v[140:143]
	v_mfma_f32_16x16x32_bf16 v[136:139], v[80:83], v[164:167], v[136:139]
	v_mfma_f32_16x16x32_bf16 v[124:127], v[68:71], v[172:175], v[124:127]
	v_mfma_f32_16x16x32_bf16 v[120:123], v[80:83], v[172:175], v[120:123]
	v_mfma_f32_16x16x32_bf16 v[108:111], v[68:71], v[180:183], v[108:111]
	v_mfma_f32_16x16x32_bf16 v[104:107], v[80:83], v[180:183], v[104:107]
	v_mfma_f32_16x16x32_bf16 v[92:95], v[68:71], v[188:191], v[92:95]
	v_mfma_f32_16x16x32_bf16 v[88:91], v[80:83], v[188:191], v[88:91]
	v_mfma_f32_16x16x32_bf16 v[132:135], v[144:147], v[160:163], v[132:135]
	v_mfma_f32_16x16x32_bf16 v[128:131], v[152:155], v[160:163], v[128:131]
	v_mfma_f32_16x16x32_bf16 v[116:119], v[144:147], v[168:171], v[116:119]
	v_mfma_f32_16x16x32_bf16 v[112:115], v[152:155], v[168:171], v[112:115]
	v_mfma_f32_16x16x32_bf16 v[100:103], v[144:147], v[176:179], v[100:103]
	v_mfma_f32_16x16x32_bf16 v[96:99], v[152:155], v[176:179], v[96:99]
	v_mfma_f32_16x16x32_bf16 v[84:87], v[144:147], v[184:187], v[84:87]
	v_mfma_f32_16x16x32_bf16 v[72:75], v[152:155], v[184:187], v[72:75]
	v_mfma_f32_16x16x32_bf16 v[132:135], v[148:151], v[164:167], v[132:135]
	v_mfma_f32_16x16x32_bf16 v[128:131], v[156:159], v[164:167], v[128:131]
	v_mfma_f32_16x16x32_bf16 v[116:119], v[148:151], v[172:175], v[116:119]
	v_mfma_f32_16x16x32_bf16 v[112:115], v[156:159], v[172:175], v[112:115]
	v_mfma_f32_16x16x32_bf16 v[100:103], v[148:151], v[180:183], v[100:103]
	v_mfma_f32_16x16x32_bf16 v[96:99], v[156:159], v[180:183], v[96:99]
	v_mfma_f32_16x16x32_bf16 v[84:87], v[148:151], v[188:191], v[84:87]
	v_mfma_f32_16x16x32_bf16 v[72:75], v[156:159], v[188:191], v[72:75]
	s_barrier
; #define PG8_STAGE(bufoff, gbase, voff) do { _Pragma("unroll") for (int _i = 0; _i < 2; ++_i) \
;         __builtin_amdgcn_global_load_lds((const unsigned*)((const char*)(gbase) + (voff)[_i]), (PG8_LAS unsigned*)(lds + (bufoff) + ldsw + _i * 8192), 16, 0, 0); } while (0)
; #define PG8_LDA(dst, b, h) do { _Pragma("unroll") for (int m = 0; m < 4; ++m) _Pragma("unroll") for (int k = 0; k < 2; ++k) dst[m][k] = *(const PG8_LAS bf16x8*)(lds + PG8_SA(b, h) + aoff + m * 2048 + k * 1024); } while (0)
; #define PG8_MMA(ai, bj, At, Bt) do { __builtin_amdgcn_s_setprio(1); _Pragma("unroll") for (int m = 0; m < 4; ++m) _Pragma("unroll") for (int n = 0; n < 2; ++n) _Pragma("unroll") for (int k = 0; k < 2; ++k) \
;         acc[ai][bj][m][n] = __builtin_amdgcn_mfma_f32_16x16x32_bf16(Bt[n][k], At[m][k], acc[ai][bj][m][n], 0, 0, 0); __builtin_amdgcn_s_setprio(0); } while (0)
; #define PG8_WAIT_V(n) asm volatile("s_waitcnt vmcnt(" #n ")" ::: "memory")
; #define PG8_WAIT_L(n) asm volatile("s_waitcnt lgkmcnt(" #n ")" ::: "memory")
; #define PG8_BAR __builtin_amdgcn_s_barrier()
; #define PG8_SCHED __builtin_amdgcn_sched_barrier(0)
; template <class Epi, class Sched, bool ALIGN_EPI = false, bool SP2 = false>
; __device__ __forceinline__ void gemm_phase(PG8_LAS unsigned char* lds, const Gemm g, const Sched& S, const Epi& E) {
;     ...
;         for (int t = 0; t < nt; t += 2) {
;     ...
;             PG8_LDA(At, 1, 1); PG8_STAGE(PG8_SB(1, 0), b3, voffB); PG8_STAGE(PG8_SB(1, 1), b3 + hstep, voffB); PG8_STAGE(PG8_SA(1, 0), a3, voffA);
;             PG8_WAIT_V(8); PG8_WAIT_L(0); PG8_BAR; PG8_MMA(1, 0, At, B0); PG8_MMA(1, 1, At, B1); PG8_BAR; PG8_SCHED;
	s_add_i32 s0, s0, s7
	v_lshl_add_u64 v[192:193], v[192:193], 0, s[42:43]
	s_mov_b32 m0, s0
	ds_read_b128 v[160:163], v251 offset:49152
	ds_read_b128 v[164:167], v251 offset:50176
	ds_read_b128 v[168:171], v251 offset:51200
	ds_read_b128 v[172:175], v251 offset:52224
	ds_read_b128 v[176:179], v251 offset:53248
	ds_read_b128 v[180:183], v251 offset:54272
	ds_read_b128 v[184:187], v251 offset:55296
	ds_read_b128 v[188:191], v251 offset:56320
	global_load_lds_dwordx4 v[192:193], off
	s_add_i32 m0, s0, 0x2000
	s_add_u32 s56, s56, 0x40080
	v_lshl_add_u64 v[192:193], v[194:195], 0, s[42:43]
	s_addc_u32 s57, s57, 0
	s_add_i32 s0, s1, s7
	global_load_lds_dwordx4 v[192:193], off
	v_lshl_add_u64 v[192:193], s[56:57], 0, v[212:213]
	s_mov_b32 m0, s0
	s_nop 0
	global_load_lds_dwordx4 v[192:193], off
	v_lshl_add_u64 v[192:193], s[56:57], 0, v[216:217]
	s_add_i32 m0, s0, 0x2000
	s_nop 0
	global_load_lds_dwordx4 v[192:193], off
	v_lshl_add_u64 v[192:193], v[196:197], 0, s[42:43]
	s_mov_b32 m0, s65
	s_nop 0
	global_load_lds_dwordx4 v[192:193], off
	v_lshl_add_u64 v[192:193], v[198:199], 0, s[42:43]
	s_mov_b32 m0, s66
	s_nop 0
	global_load_lds_dwordx4 v[192:193], off
	s_waitcnt vmcnt(8)
	s_waitcnt lgkmcnt(0)
	s_barrier
	s_waitcnt lgkmcnt(0)
	v_mfma_f32_16x16x32_bf16 v[60:63], v[64:67], v[160:163], v[60:63]
	v_mfma_f32_16x16x32_bf16 v[56:59], v[76:79], v[160:163], v[56:59]
	v_mfma_f32_16x16x32_bf16 v[44:47], v[64:67], v[168:171], v[44:47]
	v_mfma_f32_16x16x32_bf16 v[40:43], v[76:79], v[168:171], v[40:43]
	v_mfma_f32_16x16x32_bf16 v[28:31], v[64:67], v[176:179], v[28:31]
	v_mfma_f32_16x16x32_bf16 v[24:27], v[76:79], v[176:179], v[24:27]
	v_mfma_f32_16x16x32_bf16 v[12:15], v[64:67], v[184:187], v[12:15]
	v_mfma_f32_16x16x32_bf16 v[8:11], v[76:79], v[184:187], v[8:11]
	v_mfma_f32_16x16x32_bf16 v[60:63], v[68:71], v[164:167], v[60:63]
	v_mfma_f32_16x16x32_bf16 v[56:59], v[80:83], v[164:167], v[56:59]
	v_mfma_f32_16x16x32_bf16 v[44:47], v[68:71], v[172:175], v[44:47]
	v_mfma_f32_16x16x32_bf16 v[40:43], v[80:83], v[172:175], v[40:43]
	v_mfma_f32_16x16x32_bf16 v[28:31], v[68:71], v[180:183], v[28:31]
	v_mfma_f32_16x16x32_bf16 v[24:27], v[80:83], v[180:183], v[24:27]
	v_mfma_f32_16x16x32_bf16 v[12:15], v[68:71], v[188:191], v[12:15]
	v_mfma_f32_16x16x32_bf16 v[8:11], v[80:83], v[188:191], v[8:11]
	v_mfma_f32_16x16x32_bf16 v[52:55], v[144:147], v[160:163], v[52:55]
	v_mfma_f32_16x16x32_bf16 v[48:51], v[152:155], v[160:163], v[48:51]
	v_mfma_f32_16x16x32_bf16 v[36:39], v[144:147], v[168:171], v[36:39]
	v_mfma_f32_16x16x32_bf16 v[32:35], v[152:155], v[168:171], v[32:35]
	v_mfma_f32_16x16x32_bf16 v[20:23], v[144:147], v[176:179], v[20:23]
	v_mfma_f32_16x16x32_bf16 v[16:19], v[152:155], v[176:179], v[16:19]
	v_mfma_f32_16x16x32_bf16 v[4:7], v[144:147], v[184:187], v[4:7]
	v_mfma_f32_16x16x32_bf16 v[0:3], v[152:155], v[184:187], v[0:3]
	v_mfma_f32_16x16x32_bf16 v[52:55], v[148:151], v[164:167], v[52:55]
	v_mfma_f32_16x16x32_bf16 v[48:51], v[156:159], v[164:167], v[48:51]
	v_mfma_f32_16x16x32_bf16 v[36:39], v[148:151], v[172:175], v[36:39]
	v_mfma_f32_16x16x32_bf16 v[32:35], v[156:159], v[172:175], v[32:35]
	v_mfma_f32_16x16x32_bf16 v[20:23], v[148:151], v[180:183], v[20:23]
	v_mfma_f32_16x16x32_bf16 v[16:19], v[156:159], v[180:183], v[16:19]
	v_mfma_f32_16x16x32_bf16 v[4:7], v[148:151], v[188:191], v[4:7]
	v_mfma_f32_16x16x32_bf16 v[0:3], v[156:159], v[188:191], v[0:3]
	s_barrier
	s_add_i32 s77, s77, 2
	s_add_u32 s54, s54, 0x100
	s_addc_u32 s55, s55, 0
	s_add_u32 s75, s75, 0x100
	s_addc_u32 s76, s76, 0
	s_cmp_gt_u32 s77, 13
	s_cbranch_scc0 .LBB0_458
	s_setprio 0
	s_and_b64 vcc, exec, s[44:45]
	s_cbranch_vccz .LBB0_461
	s_barrier

; #define PG8_STAGE(bufoff, gbase, voff) do { _Pragma("unroll") for (int _i = 0; _i < 2; ++_i) \
;         __builtin_amdgcn_global_load_lds((const unsigned*)((const char*)(gbase) + (voff)[_i]), (PG8_LAS unsigned*)(lds + (bufoff) + ldsw + _i * 8192), 16, 0, 0); } while (0)
; #define PG8_LDA(dst, b, h) do { _Pragma("unroll") for (int m = 0; m < 4; ++m) _Pragma("unroll") for (int k = 0; k < 2; ++k) dst[m][k] = *(const PG8_LAS bf16x8*)(lds + PG8_SA(b, h) + aoff + m * 2048 + k * 1024); } while (0)
; #define PG8_LDB(dst, b, h) do { _Pragma("unroll") for (int n = 0; n < 2; ++n) _Pragma("unroll") for (int k = 0; k < 2; ++k) dst[n][k] = *(const PG8_LAS bf16x8*)(lds + PG8_SB(b, h) + boff + n * 2048 + k * 1024); } while (0)
; #define PG8_MMA(ai, bj, At, Bt) do { __builtin_amdgcn_s_setprio(1); _Pragma("unroll") for (int m = 0; m < 4; ++m) _Pragma("unroll") for (int n = 0; n < 2; ++n) _Pragma("unroll") for (int k = 0; k < 2; ++k) \
;         acc[ai][bj][m][n] = __builtin_amdgcn_mfma_f32_16x16x32_bf16(Bt[n][k], At[m][k], acc[ai][bj][m][n], 0, 0, 0); __builtin_amdgcn_s_setprio(0); } while (0)
; #define PG8_WAIT_V(n) asm volatile("s_waitcnt vmcnt(" #n ")" ::: "memory")
; #define PG8_WAIT_L(n) asm volatile("s_waitcnt lgkmcnt(" #n ")" ::: "memory")
; #define PG8_BAR __builtin_amdgcn_s_barrier()
; #define PG8_SCHED __builtin_amdgcn_sched_barrier(0)
; template <class Epi, class Sched, bool ALIGN_EPI = false, bool SP2 = false>
; __device__ __forceinline__ void gemm_phase(PG8_LAS unsigned char* lds, const Gemm g, const Sched& S, const Epi& E) {
;     ...
;             PG8_LDB(B0, 0, 0); PG8_LDB(B1, 0, 1); PG8_SCHED; PG8_LDA(At, 0, 0); PG8_STAGE(PG8_SA(1, 1), a1 + hstep, voffA);
;             PG8_WAIT_V(8); PG8_WAIT_L(0); PG8_BAR; PG8_MMA(0, 0, At, B0); PG8_MMA(0, 1, At, B1); PG8_BAR; PG8_SCHED;
;     ...
;         for (int a = 0; a < 2; ++a)
; #pragma unroll
;             for (int b = 0; b < 2; ++b)
; #pragma unroll
;                 for (int m = 0; m < 4; ++m)
; #pragma unroll
;                     for (int n = 0; n < 2; ++n) acc[a][b][m][n] = (f32x4){0.f, 0.f, 0.f, 0.f};
.LBB0_673:
	s_add_u32 s22, s22, 0xb0080
	s_addc_u32 s23, s23, 0
	s_add_u32 s50, s24, 0x100
	v_mov_b32_e32 v0, 0
	s_addc_u32 s51, s25, 0
	s_mov_b32 s52, -2
	v_mov_b32_e32 v1, v0
	v_mov_b32_e32 v2, v0
	v_mov_b32_e32 v3, v0
	v_mov_b32_e32 v4, v0
	v_mov_b32_e32 v5, v0
	v_mov_b32_e32 v6, v0
	v_mov_b32_e32 v7, v0
	v_mov_b32_e32 v12, v0
	v_mov_b32_e32 v13, v0
	v_mov_b32_e32 v14, v0
	v_mov_b32_e32 v15, v0
	v_mov_b32_e32 v20, v0
	v_mov_b32_e32 v21, v0
	v_mov_b32_e32 v22, v0
	v_mov_b32_e32 v23, v0
	v_mov_b32_e32 v28, v0
	v_mov_b32_e32 v29, v0
	v_mov_b32_e32 v30, v0
	v_mov_b32_e32 v31, v0
	v_mov_b32_e32 v36, v0
	v_mov_b32_e32 v37, v0
	v_mov_b32_e32 v38, v0
	v_mov_b32_e32 v39, v0
	v_mov_b32_e32 v44, v0
	v_mov_b32_e32 v45, v0
	v_mov_b32_e32 v46, v0
	v_mov_b32_e32 v47, v0
	v_mov_b32_e32 v52, v0
	v_mov_b32_e32 v53, v0
	v_mov_b32_e32 v54, v0
	v_mov_b32_e32 v55, v0
	v_mov_b32_e32 v8, v0
	v_mov_b32_e32 v9, v0
	v_mov_b32_e32 v10, v0
	v_mov_b32_e32 v11, v0
	v_mov_b32_e32 v16, v0
	v_mov_b32_e32 v17, v0
	v_mov_b32_e32 v18, v0
	v_mov_b32_e32 v19, v0
	v_mov_b32_e32 v24, v0
	v_mov_b32_e32 v25, v0
	v_mov_b32_e32 v26, v0
	v_mov_b32_e32 v27, v0
	v_mov_b32_e32 v32, v0
	v_mov_b32_e32 v33, v0
	v_mov_b32_e32 v34, v0
	v_mov_b32_e32 v35, v0
	v_mov_b32_e32 v40, v0
	v_mov_b32_e32 v41, v0
	v_mov_b32_e32 v42, v0
	v_mov_b32_e32 v43, v0
	v_mov_b32_e32 v48, v0
	v_mov_b32_e32 v49, v0
	v_mov_b32_e32 v50, v0
	v_mov_b32_e32 v51, v0
	v_mov_b32_e32 v56, v0
	v_mov_b32_e32 v57, v0
	v_mov_b32_e32 v58, v0
	v_mov_b32_e32 v59, v0
	v_mov_b32_e32 v60, v0
	v_mov_b32_e32 v61, v0
	v_mov_b32_e32 v62, v0
	v_mov_b32_e32 v63, v0
	v_mov_b32_e32 v64, v0
	v_mov_b32_e32 v65, v0
	v_mov_b32_e32 v66, v0
	v_mov_b32_e32 v67, v0
	v_mov_b32_e32 v68, v0
	v_mov_b32_e32 v69, v0
	v_mov_b32_e32 v70, v0
	v_mov_b32_e32 v71, v0
	v_mov_b32_e32 v76, v0
	v_mov_b32_e32 v77, v0
	v_mov_b32_e32 v78, v0
	v_mov_b32_e32 v79, v0
	v_mov_b32_e32 v84, v0
	v_mov_b32_e32 v85, v0
	v_mov_b32_e32 v86, v0
	v_mov_b32_e32 v87, v0
	v_mov_b32_e32 v92, v0
	v_mov_b32_e32 v93, v0
	v_mov_b32_e32 v94, v0
	v_mov_b32_e32 v95, v0
	v_mov_b32_e32 v100, v0
	v_mov_b32_e32 v101, v0
	v_mov_b32_e32 v102, v0
	v_mov_b32_e32 v103, v0
	v_mov_b32_e32 v104, v0
	v_mov_b32_e32 v105, v0
	v_mov_b32_e32 v106, v0
	v_mov_b32_e32 v107, v0
	v_mov_b32_e32 v108, v0
	v_mov_b32_e32 v109, v0
	v_mov_b32_e32 v110, v0
	v_mov_b32_e32 v111, v0
	v_mov_b32_e32 v72, v0
	v_mov_b32_e32 v73, v0
	v_mov_b32_e32 v74, v0
	v_mov_b32_e32 v75, v0
	v_mov_b32_e32 v80, v0
	v_mov_b32_e32 v81, v0
	v_mov_b32_e32 v82, v0
	v_mov_b32_e32 v83, v0
	v_mov_b32_e32 v88, v0
	v_mov_b32_e32 v89, v0
	v_mov_b32_e32 v90, v0
	v_mov_b32_e32 v91, v0
	v_mov_b32_e32 v96, v0
	v_mov_b32_e32 v97, v0
	v_mov_b32_e32 v98, v0
	v_mov_b32_e32 v99, v0
	v_mov_b32_e32 v112, v0
	v_mov_b32_e32 v113, v0
	v_mov_b32_e32 v114, v0
	v_mov_b32_e32 v115, v0
	v_mov_b32_e32 v116, v0
	v_mov_b32_e32 v117, v0
	v_mov_b32_e32 v118, v0
	v_mov_b32_e32 v119, v0
	v_mov_b32_e32 v120, v0
	v_mov_b32_e32 v121, v0
	v_mov_b32_e32 v122, v0
	v_mov_b32_e32 v123, v0
	v_mov_b32_e32 v124, v0
	v_mov_b32_e32 v125, v0
	v_mov_b32_e32 v126, v0
	v_mov_b32_e32 v127, v0
	v_readfirstlane_b32 s32, v208
	s_cmp_ge_u32 s32, 256
	s_cbranch_scc0 .Lprio7_done
	s_setprio 1
.Lprio7_done:
.LBB0_674:
	ds_read_b128 v[128:131], v171
	ds_read_b128 v[132:135], v171 offset:1024
	ds_read_b128 v[136:139], v171 offset:2048
	ds_read_b128 v[140:143], v171 offset:3072
	ds_read_b128 v[162:165], v172
	ds_read_b128 v[174:177], v172 offset:1024
	ds_read_b128 v[178:181], v172 offset:2048
	ds_read_b128 v[182:185], v172 offset:3072
	s_add_u32 s24, s22, 0xfff50080
	s_addc_u32 s25, s23, -1
	s_cmp_eq_u32 s52, 40
	s_cselect_b32 s29, s5, s25
	s_cselect_b32 s28, s4, s24
	s_cselect_b32 s25, s21, s51
	s_cselect_b32 s24, s20, s50
	v_lshl_add_u64 v[166:167], s[22:23], 0, v[154:155]
	s_add_i32 m0, s35, 0xc000
	ds_read_b128 v[186:189], v173
	ds_read_b128 v[190:193], v173 offset:1024
	ds_read_b128 v[194:197], v173 offset:2048
	ds_read_b128 v[198:201], v173 offset:3072
	ds_read_b128 v[202:205], v173 offset:4096
	ds_read_b128 v[206:209], v173 offset:5120
	ds_read_b128 v[210:213], v173 offset:6144
	ds_read_b128 v[214:217], v173 offset:7168
	global_load_lds_dwordx4 v[166:167], off
	v_lshl_add_u64 v[166:167], s[22:23], 0, v[156:157]
	s_add_i32 m0, s35, 0xe000
	s_nop 0
	global_load_lds_dwordx4 v[166:167], off
	s_waitcnt vmcnt(8)
	s_waitcnt lgkmcnt(0)
	s_barrier
	s_waitcnt lgkmcnt(0)
	v_mfma_f32_16x16x32_bf16 v[124:127], v[128:131], v[186:189], v[124:127]
	v_mfma_f32_16x16x32_bf16 v[120:123], v[136:139], v[186:189], v[120:123]
	v_mfma_f32_16x16x32_bf16 v[116:119], v[128:131], v[194:197], v[116:119]
	v_mfma_f32_16x16x32_bf16 v[112:115], v[136:139], v[194:197], v[112:115]
	v_mfma_f32_16x16x32_bf16 v[96:99], v[128:131], v[202:205], v[96:99]
	v_mfma_f32_16x16x32_bf16 v[88:91], v[136:139], v[202:205], v[88:91]
	v_mfma_f32_16x16x32_bf16 v[80:83], v[128:131], v[210:213], v[80:83]
	v_mfma_f32_16x16x32_bf16 v[72:75], v[136:139], v[210:213], v[72:75]
	v_mfma_f32_16x16x32_bf16 v[124:127], v[132:135], v[190:193], v[124:127]
	v_mfma_f32_16x16x32_bf16 v[120:123], v[140:143], v[190:193], v[120:123]
	v_mfma_f32_16x16x32_bf16 v[116:119], v[132:135], v[198:201], v[116:119]
	v_mfma_f32_16x16x32_bf16 v[112:115], v[140:143], v[198:201], v[112:115]
	v_mfma_f32_16x16x32_bf16 v[96:99], v[132:135], v[206:209], v[96:99]
	v_mfma_f32_16x16x32_bf16 v[88:91], v[140:143], v[206:209], v[88:91]
	v_mfma_f32_16x16x32_bf16 v[80:83], v[132:135], v[214:217], v[80:83]
	v_mfma_f32_16x16x32_bf16 v[72:75], v[140:143], v[214:217], v[72:75]
	v_mfma_f32_16x16x32_bf16 v[108:111], v[162:165], v[186:189], v[108:111]
	v_mfma_f32_16x16x32_bf16 v[104:107], v[178:181], v[186:189], v[104:107]
	v_mfma_f32_16x16x32_bf16 v[100:103], v[162:165], v[194:197], v[100:103]
	v_mfma_f32_16x16x32_bf16 v[92:95], v[178:181], v[194:197], v[92:95]
	v_mfma_f32_16x16x32_bf16 v[84:87], v[162:165], v[202:205], v[84:87]
	v_mfma_f32_16x16x32_bf16 v[76:79], v[178:181], v[202:205], v[76:79]
	v_mfma_f32_16x16x32_bf16 v[68:71], v[162:165], v[210:213], v[68:71]
	v_mfma_f32_16x16x32_bf16 v[64:67], v[178:181], v[210:213], v[64:67]
	v_mfma_f32_16x16x32_bf16 v[108:111], v[174:177], v[190:193], v[108:111]
	v_mfma_f32_16x16x32_bf16 v[104:107], v[182:185], v[190:193], v[104:107]
	v_mfma_f32_16x16x32_bf16 v[100:103], v[174:177], v[198:201], v[100:103]
	v_mfma_f32_16x16x32_bf16 v[92:95], v[182:185], v[198:201], v[92:95]
	v_mfma_f32_16x16x32_bf16 v[84:87], v[174:177], v[206:209], v[84:87]
	v_mfma_f32_16x16x32_bf16 v[76:79], v[182:185], v[206:209], v[76:79]
	v_mfma_f32_16x16x32_bf16 v[68:71], v[174:177], v[214:217], v[68:71]
	v_mfma_f32_16x16x32_bf16 v[64:67], v[182:185], v[214:217], v[64:67]
	s_barrier
; #define PG8_STAGE(bufoff, gbase, voff) do { _Pragma("unroll") for (int _i = 0; _i < 2; ++_i) \
;         __builtin_amdgcn_global_load_lds((const unsigned*)((const char*)(gbase) + (voff)[_i]), (PG8_LAS unsigned*)(lds + (bufoff) + ldsw + _i * 8192), 16, 0, 0); } while (0)
; #define PG8_LDA(dst, b, h) do { _Pragma("unroll") for (int m = 0; m < 4; ++m) _Pragma("unroll") for (int k = 0; k < 2; ++k) dst[m][k] = *(const PG8_LAS bf16x8*)(lds + PG8_SA(b, h) + aoff + m * 2048 + k * 1024); } while (0)
; #define PG8_LDB(dst, b, h) do { _Pragma("unroll") for (int n = 0; n < 2; ++n) _Pragma("unroll") for (int k = 0; k < 2; ++k) dst[n][k] = *(const PG8_LAS bf16x8*)(lds + PG8_SB(b, h) + boff + n * 2048 + k * 1024); } while (0)
; #define PG8_MMA(ai, bj, At, Bt) do { __builtin_amdgcn_s_setprio(1); _Pragma("unroll") for (int m = 0; m < 4; ++m) _Pragma("unroll") for (int n = 0; n < 2; ++n) _Pragma("unroll") for (int k = 0; k < 2; ++k) \
;         acc[ai][bj][m][n] = __builtin_amdgcn_mfma_f32_16x16x32_bf16(Bt[n][k], At[m][k], acc[ai][bj][m][n], 0, 0, 0); __builtin_amdgcn_s_setprio(0); } while (0)
; #define PG8_WAIT_V(n) asm volatile("s_waitcnt vmcnt(" #n ")" ::: "memory")
; #define PG8_WAIT_L(n) asm volatile("s_waitcnt lgkmcnt(" #n ")" ::: "memory")
; #define PG8_BAR __builtin_amdgcn_s_barrier()
; #define PG8_SCHED __builtin_amdgcn_sched_barrier(0)
; template <class Epi, class Sched, bool ALIGN_EPI = false, bool SP2 = false>
; __device__ __forceinline__ void gemm_phase(PG8_LAS unsigned char* lds, const Gemm g, const Sched& S, const Epi& E) {
;     ...
;             PG8_WAIT_V(8); PG8_WAIT_L(0); PG8_BAR; PG8_MMA(0, 0, At, B0); PG8_MMA(0, 1, At, B1); PG8_BAR; PG8_SCHED;
;             PG8_LDA(At, 0, 1); PG8_STAGE(PG8_SB(0, 0), b2, voffB); PG8_STAGE(PG8_SB(0, 1), b2 + hstep, voffB); PG8_STAGE(PG8_SA(0, 0), a2, voffA);
;             PG8_WAIT_V(8); PG8_WAIT_L(0); PG8_BAR; PG8_MMA(1, 0, At, B0); PG8_MMA(1, 1, At, B1); PG8_BAR; PG8_SCHED;
;             PG8_LDB(B0, 1, 0); PG8_LDB(B1, 1, 1); PG8_SCHED; PG8_LDA(At, 1, 0); PG8_STAGE(PG8_SA(0, 1), a2 + hstep, voffA);
;             PG8_WAIT_V(8); PG8_WAIT_L(0); PG8_BAR; PG8_MMA(0, 0, At, B0); PG8_MMA(0, 1, At, B1); PG8_BAR; PG8_SCHED;
	s_add_i32 s53, s43, s34
	v_lshl_add_u64 v[166:167], s[24:25], 0, v[146:147]
	s_mov_b32 m0, s53
	ds_read_b128 v[186:189], v173 offset:16384
	ds_read_b128 v[190:193], v173 offset:17408
	ds_read_b128 v[194:197], v173 offset:18432
	ds_read_b128 v[198:201], v173 offset:19456
	ds_read_b128 v[202:205], v173 offset:20480
	ds_read_b128 v[206:209], v173 offset:21504
	ds_read_b128 v[210:213], v173 offset:22528
	ds_read_b128 v[214:217], v173 offset:23552
	global_load_lds_dwordx4 v[166:167], off
	s_add_i32 m0, s53, 0x2000
	s_add_u32 s54, s24, 0xb0000
	v_lshl_add_u64 v[218:219], s[24:25], 0, v[150:151]
	s_addc_u32 s55, s25, 0
	s_add_i32 s53, s44, s34
	global_load_lds_dwordx4 v[218:219], off
	v_lshl_add_u64 v[220:221], s[54:55], 0, v[146:147]
	s_mov_b32 m0, s53
	v_lshl_add_u64 v[222:223], s[28:29], 0, v[148:149]
	global_load_lds_dwordx4 v[220:221], off
	v_lshl_add_u64 v[220:221], s[54:55], 0, v[150:151]
	s_add_i32 m0, s53, 0x2000
	s_nop 0
	global_load_lds_dwordx4 v[220:221], off
	v_lshl_add_u64 v[220:221], s[28:29], 0, v[144:145]
	s_mov_b32 m0, s35
	s_nop 0
	global_load_lds_dwordx4 v[220:221], off
	s_mov_b32 m0, s36
	s_nop 0
	global_load_lds_dwordx4 v[222:223], off
	s_waitcnt vmcnt(8)
	s_waitcnt lgkmcnt(0)
	s_barrier
	s_waitcnt lgkmcnt(0)
	v_mfma_f32_16x16x32_bf16 v[60:63], v[128:131], v[186:189], v[60:63]
	v_mfma_f32_16x16x32_bf16 v[56:59], v[136:139], v[186:189], v[56:59]
	v_mfma_f32_16x16x32_bf16 v[48:51], v[128:131], v[194:197], v[48:51]
	v_mfma_f32_16x16x32_bf16 v[40:43], v[136:139], v[194:197], v[40:43]
	v_mfma_f32_16x16x32_bf16 v[32:35], v[128:131], v[202:205], v[32:35]
	v_mfma_f32_16x16x32_bf16 v[24:27], v[136:139], v[202:205], v[24:27]
	v_mfma_f32_16x16x32_bf16 v[16:19], v[128:131], v[210:213], v[16:19]
	v_mfma_f32_16x16x32_bf16 v[8:11], v[136:139], v[210:213], v[8:11]
	v_mfma_f32_16x16x32_bf16 v[60:63], v[132:135], v[190:193], v[60:63]
	v_mfma_f32_16x16x32_bf16 v[56:59], v[140:143], v[190:193], v[56:59]
	v_mfma_f32_16x16x32_bf16 v[48:51], v[132:135], v[198:201], v[48:51]
	v_mfma_f32_16x16x32_bf16 v[40:43], v[140:143], v[198:201], v[40:43]
	v_mfma_f32_16x16x32_bf16 v[32:35], v[132:135], v[206:209], v[32:35]
	v_mfma_f32_16x16x32_bf16 v[24:27], v[140:143], v[206:209], v[24:27]
	v_mfma_f32_16x16x32_bf16 v[16:19], v[132:135], v[214:217], v[16:19]
	v_mfma_f32_16x16x32_bf16 v[8:11], v[140:143], v[214:217], v[8:11]
	v_mfma_f32_16x16x32_bf16 v[52:55], v[162:165], v[186:189], v[52:55]
	v_mfma_f32_16x16x32_bf16 v[44:47], v[178:181], v[186:189], v[44:47]
	v_mfma_f32_16x16x32_bf16 v[36:39], v[162:165], v[194:197], v[36:39]
	v_mfma_f32_16x16x32_bf16 v[28:31], v[178:181], v[194:197], v[28:31]
	v_mfma_f32_16x16x32_bf16 v[20:23], v[162:165], v[202:205], v[20:23]
	v_mfma_f32_16x16x32_bf16 v[12:15], v[178:181], v[202:205], v[12:15]
	v_mfma_f32_16x16x32_bf16 v[4:7], v[162:165], v[210:213], v[4:7]
	v_mfma_f32_16x16x32_bf16 v[0:3], v[178:181], v[210:213], v[0:3]
	v_mfma_f32_16x16x32_bf16 v[52:55], v[174:177], v[190:193], v[52:55]
	v_mfma_f32_16x16x32_bf16 v[44:47], v[182:185], v[190:193], v[44:47]
	v_mfma_f32_16x16x32_bf16 v[36:39], v[174:177], v[198:201], v[36:39]
	v_mfma_f32_16x16x32_bf16 v[28:31], v[182:185], v[198:201], v[28:31]
	v_mfma_f32_16x16x32_bf16 v[20:23], v[174:177], v[206:209], v[20:23]
	v_mfma_f32_16x16x32_bf16 v[12:15], v[182:185], v[206:209], v[12:15]
	v_mfma_f32_16x16x32_bf16 v[4:7], v[174:177], v[214:217], v[4:7]
	v_mfma_f32_16x16x32_bf16 v[0:3], v[182:185], v[214:217], v[0:3]
	s_barrier
	s_add_i32 s53, 0, 0x18000
	s_add_i32 s54, 0, 0x1c000
	v_add_u32_e32 v140, s53, v168
	v_add_u32_e32 v152, s54, v168
	ds_read_b128 v[128:131], v140
	ds_read_b128 v[132:135], v140 offset:1024
	ds_read_b128 v[136:139], v140 offset:2048
	ds_read_b128 v[140:143], v140 offset:3072
	ds_read_b128 v[162:165], v152
	ds_read_b128 v[174:177], v152 offset:1024
	ds_read_b128 v[178:181], v152 offset:2048
	ds_read_b128 v[182:185], v152 offset:3072
	s_add_u32 s28, s28, 0xb0000
	s_addc_u32 s29, s29, 0
	s_mov_b32 m0, s37
	v_lshl_add_u64 v[224:225], s[28:29], 0, v[144:145]
	ds_read_b128 v[186:189], v173 offset:32768
	ds_read_b128 v[190:193], v173 offset:33792
	ds_read_b128 v[194:197], v173 offset:34816
	ds_read_b128 v[198:201], v173 offset:35840
	ds_read_b128 v[202:205], v173 offset:36864
	ds_read_b128 v[206:209], v173 offset:37888
	ds_read_b128 v[210:213], v173 offset:38912
	ds_read_b128 v[214:217], v173 offset:39936
	global_load_lds_dwordx4 v[224:225], off
	v_lshl_add_u64 v[224:225], s[28:29], 0, v[148:149]
	s_mov_b32 m0, s38
	s_nop 0
	global_load_lds_dwordx4 v[224:225], off
	s_waitcnt vmcnt(8)
	s_waitcnt lgkmcnt(0)
	s_barrier
; #define PG8_STAGE(bufoff, gbase, voff) do { _Pragma("unroll") for (int _i = 0; _i < 2; ++_i) \
;         __builtin_amdgcn_global_load_lds((const unsigned*)((const char*)(gbase) + (voff)[_i]), (PG8_LAS unsigned*)(lds + (bufoff) + ldsw + _i * 8192), 16, 0, 0); } while (0)
; #define PG8_LDA(dst, b, h) do { _Pragma("unroll") for (int m = 0; m < 4; ++m) _Pragma("unroll") for (int k = 0; k < 2; ++k) dst[m][k] = *(const PG8_LAS bf16x8*)(lds + PG8_SA(b, h) + aoff + m * 2048 + k * 1024); } while (0)
; #define PG8_MMA(ai, bj, At, Bt) do { __builtin_amdgcn_s_setprio(1); _Pragma("unroll") for (int m = 0; m < 4; ++m) _Pragma("unroll") for (int n = 0; n < 2; ++n) _Pragma("unroll") for (int k = 0; k < 2; ++k) \
;         acc[ai][bj][m][n] = __builtin_amdgcn_mfma_f32_16x16x32_bf16(Bt[n][k], At[m][k], acc[ai][bj][m][n], 0, 0, 0); __builtin_amdgcn_s_setprio(0); } while (0)
; #define PG8_WAIT_V(n) asm volatile("s_waitcnt vmcnt(" #n ")" ::: "memory")
; #define PG8_WAIT_L(n) asm volatile("s_waitcnt lgkmcnt(" #n ")" ::: "memory")
; #define PG8_BAR __builtin_amdgcn_s_barrier()
; #define PG8_SCHED __builtin_amdgcn_sched_barrier(0)
; template <class Epi, class Sched, bool ALIGN_EPI = false, bool SP2 = false>
; __device__ __forceinline__ void gemm_phase(PG8_LAS unsigned char* lds, const Gemm g, const Sched& S, const Epi& E) {
;     ...
;         for (int t = 0; t < nt; t += 2) {
;     ...
;             PG8_WAIT_V(8); PG8_WAIT_L(0); PG8_BAR; PG8_MMA(0, 0, At, B0); PG8_MMA(0, 1, At, B1); PG8_BAR; PG8_SCHED;
;             PG8_LDA(At, 1, 1); PG8_STAGE(PG8_SB(1, 0), b3, voffB); PG8_STAGE(PG8_SB(1, 1), b3 + hstep, voffB); PG8_STAGE(PG8_SA(1, 0), a3, voffA);
;             PG8_WAIT_V(8); PG8_WAIT_L(0); PG8_BAR; PG8_MMA(1, 0, At, B0); PG8_MMA(1, 1, At, B1); PG8_BAR; PG8_SCHED;
	s_waitcnt lgkmcnt(0)
	v_mfma_f32_16x16x32_bf16 v[124:127], v[128:131], v[186:189], v[124:127]
	v_mfma_f32_16x16x32_bf16 v[120:123], v[136:139], v[186:189], v[120:123]
	v_mfma_f32_16x16x32_bf16 v[116:119], v[128:131], v[194:197], v[116:119]
	v_mfma_f32_16x16x32_bf16 v[112:115], v[136:139], v[194:197], v[112:115]
	v_mfma_f32_16x16x32_bf16 v[96:99], v[128:131], v[202:205], v[96:99]
	v_mfma_f32_16x16x32_bf16 v[88:91], v[136:139], v[202:205], v[88:91]
	v_mfma_f32_16x16x32_bf16 v[80:83], v[128:131], v[210:213], v[80:83]
	v_mfma_f32_16x16x32_bf16 v[72:75], v[136:139], v[210:213], v[72:75]
	v_mfma_f32_16x16x32_bf16 v[124:127], v[132:135], v[190:193], v[124:127]
	v_mfma_f32_16x16x32_bf16 v[120:123], v[140:143], v[190:193], v[120:123]
	v_mfma_f32_16x16x32_bf16 v[116:119], v[132:135], v[198:201], v[116:119]
	v_mfma_f32_16x16x32_bf16 v[112:115], v[140:143], v[198:201], v[112:115]
	v_mfma_f32_16x16x32_bf16 v[96:99], v[132:135], v[206:209], v[96:99]
	v_mfma_f32_16x16x32_bf16 v[88:91], v[140:143], v[206:209], v[88:91]
	v_mfma_f32_16x16x32_bf16 v[80:83], v[132:135], v[214:217], v[80:83]
	v_mfma_f32_16x16x32_bf16 v[72:75], v[140:143], v[214:217], v[72:75]
	v_mfma_f32_16x16x32_bf16 v[108:111], v[162:165], v[186:189], v[108:111]
	v_mfma_f32_16x16x32_bf16 v[104:107], v[178:181], v[186:189], v[104:107]
	v_mfma_f32_16x16x32_bf16 v[100:103], v[162:165], v[194:197], v[100:103]
	v_mfma_f32_16x16x32_bf16 v[92:95], v[178:181], v[194:197], v[92:95]
	v_mfma_f32_16x16x32_bf16 v[84:87], v[162:165], v[202:205], v[84:87]
	v_mfma_f32_16x16x32_bf16 v[76:79], v[178:181], v[202:205], v[76:79]
	v_mfma_f32_16x16x32_bf16 v[68:71], v[162:165], v[210:213], v[68:71]
	v_mfma_f32_16x16x32_bf16 v[64:67], v[178:181], v[210:213], v[64:67]
	v_mfma_f32_16x16x32_bf16 v[108:111], v[174:177], v[190:193], v[108:111]
	v_mfma_f32_16x16x32_bf16 v[104:107], v[182:185], v[190:193], v[104:107]
	v_mfma_f32_16x16x32_bf16 v[100:103], v[174:177], v[198:201], v[100:103]
	v_mfma_f32_16x16x32_bf16 v[92:95], v[182:185], v[198:201], v[92:95]
	v_mfma_f32_16x16x32_bf16 v[84:87], v[174:177], v[206:209], v[84:87]
	v_mfma_f32_16x16x32_bf16 v[76:79], v[182:185], v[206:209], v[76:79]
	v_mfma_f32_16x16x32_bf16 v[68:71], v[174:177], v[214:217], v[68:71]
	v_mfma_f32_16x16x32_bf16 v[64:67], v[182:185], v[214:217], v[64:67]
	s_barrier
	s_add_i32 s28, s53, s34
	v_lshl_add_u64 v[166:167], v[166:167], 0, s[14:15]
	s_mov_b32 m0, s28
	ds_read_b128 v[186:189], v173 offset:49152
	ds_read_b128 v[190:193], v173 offset:50176
	ds_read_b128 v[194:197], v173 offset:51200
	ds_read_b128 v[198:201], v173 offset:52224
	ds_read_b128 v[202:205], v173 offset:53248
	ds_read_b128 v[206:209], v173 offset:54272
	ds_read_b128 v[210:213], v173 offset:55296
	ds_read_b128 v[214:217], v173 offset:56320
	global_load_lds_dwordx4 v[166:167], off
	s_add_i32 m0, s28, 0x2000
	s_add_u32 s24, s24, 0xb0080
	v_lshl_add_u64 v[166:167], v[218:219], 0, s[14:15]
	s_addc_u32 s25, s25, 0
	s_add_i32 s28, s54, s34
	global_load_lds_dwordx4 v[166:167], off
	v_lshl_add_u64 v[166:167], s[24:25], 0, v[146:147]
	s_mov_b32 m0, s28
	s_nop 0
	global_load_lds_dwordx4 v[166:167], off
	v_lshl_add_u64 v[166:167], s[24:25], 0, v[150:151]
	s_add_i32 m0, s28, 0x2000
	s_nop 0
	global_load_lds_dwordx4 v[166:167], off
	v_lshl_add_u64 v[166:167], v[220:221], 0, s[14:15]
	s_mov_b32 m0, s40
	s_nop 0
	global_load_lds_dwordx4 v[166:167], off
	v_lshl_add_u64 v[166:167], v[222:223], 0, s[14:15]
	s_mov_b32 m0, s41
	s_nop 0
	global_load_lds_dwordx4 v[166:167], off
	s_waitcnt vmcnt(8)
	s_waitcnt lgkmcnt(0)
	s_barrier
	s_waitcnt lgkmcnt(0)
	v_mfma_f32_16x16x32_bf16 v[60:63], v[128:131], v[186:189], v[60:63]
	v_mfma_f32_16x16x32_bf16 v[56:59], v[136:139], v[186:189], v[56:59]
	v_mfma_f32_16x16x32_bf16 v[48:51], v[128:131], v[194:197], v[48:51]
	v_mfma_f32_16x16x32_bf16 v[40:43], v[136:139], v[194:197], v[40:43]
	v_mfma_f32_16x16x32_bf16 v[32:35], v[128:131], v[202:205], v[32:35]
	v_mfma_f32_16x16x32_bf16 v[24:27], v[136:139], v[202:205], v[24:27]
	v_mfma_f32_16x16x32_bf16 v[16:19], v[128:131], v[210:213], v[16:19]
	v_mfma_f32_16x16x32_bf16 v[8:11], v[136:139], v[210:213], v[8:11]
	v_mfma_f32_16x16x32_bf16 v[60:63], v[132:135], v[190:193], v[60:63]
	v_mfma_f32_16x16x32_bf16 v[56:59], v[140:143], v[190:193], v[56:59]
	v_mfma_f32_16x16x32_bf16 v[48:51], v[132:135], v[198:201], v[48:51]
	v_mfma_f32_16x16x32_bf16 v[40:43], v[140:143], v[198:201], v[40:43]
	v_mfma_f32_16x16x32_bf16 v[32:35], v[132:135], v[206:209], v[32:35]
	v_mfma_f32_16x16x32_bf16 v[24:27], v[140:143], v[206:209], v[24:27]
	v_mfma_f32_16x16x32_bf16 v[16:19], v[132:135], v[214:217], v[16:19]
	v_mfma_f32_16x16x32_bf16 v[8:11], v[140:143], v[214:217], v[8:11]
	v_mfma_f32_16x16x32_bf16 v[52:55], v[162:165], v[186:189], v[52:55]
	v_mfma_f32_16x16x32_bf16 v[44:47], v[178:181], v[186:189], v[44:47]
	v_mfma_f32_16x16x32_bf16 v[36:39], v[162:165], v[194:197], v[36:39]
	v_mfma_f32_16x16x32_bf16 v[28:31], v[178:181], v[194:197], v[28:31]
	v_mfma_f32_16x16x32_bf16 v[20:23], v[162:165], v[202:205], v[20:23]
	v_mfma_f32_16x16x32_bf16 v[12:15], v[178:181], v[202:205], v[12:15]
	v_mfma_f32_16x16x32_bf16 v[4:7], v[162:165], v[210:213], v[4:7]
	v_mfma_f32_16x16x32_bf16 v[0:3], v[178:181], v[210:213], v[0:3]
	v_mfma_f32_16x16x32_bf16 v[52:55], v[174:177], v[190:193], v[52:55]
	v_mfma_f32_16x16x32_bf16 v[44:47], v[182:185], v[190:193], v[44:47]
	v_mfma_f32_16x16x32_bf16 v[36:39], v[174:177], v[198:201], v[36:39]
	v_mfma_f32_16x16x32_bf16 v[28:31], v[182:185], v[198:201], v[28:31]
	v_mfma_f32_16x16x32_bf16 v[20:23], v[174:177], v[206:209], v[20:23]
	v_mfma_f32_16x16x32_bf16 v[12:15], v[182:185], v[206:209], v[12:15]
	v_mfma_f32_16x16x32_bf16 v[4:7], v[174:177], v[214:217], v[4:7]
	v_mfma_f32_16x16x32_bf16 v[0:3], v[182:185], v[214:217], v[0:3]
	s_barrier
	s_add_i32 s52, s52, 2
	s_add_u32 s22, s22, 0x100
	s_addc_u32 s23, s23, 0
	s_add_u32 s50, s50, 0x100
	s_addc_u32 s51, s51, 0
	s_cmp_gt_u32 s52, 41
	s_cbranch_scc0 .LBB0_674
	s_setprio 0
	s_and_b64 vcc, exec, s[16:17]
	s_cbranch_vccz .LBB0_677
	s_barrier
